# K-loop MFMA order variant 32_chain_b (+ load segments without VALU copies)
# speedup vs baseline: 1.0200x; 1.0008x over previous
; #define PG8_STAGE(bufoff, gbase, voff) do { const char* gb_ = (const char*)(gbase); asm volatile("" : "+s"(gb_)); _Pragma("unroll") for (int _i = 0; _i < 2; ++_i) { unsigned vo_ = (voff)[_i]; asm volatile("" : "+v"(vo_));        \
;         __builtin_amdgcn_global_load_lds((const unsigned*)(gb_ + vo_), (PG8_LAS unsigned*)(lds + (bufoff) + ldsw + _i * 8192), 16, 0, 0); } } while (0)
; #define PG8_LDA(dst, b, h) do { _Pragma("unroll") for (int m = 0; m < 4; ++m) _Pragma("unroll") for (int k = 0; k < 2; ++k) dst[m][k] = *(const PG8_LAS bf16x8*)(lds + PG8_SA(b, h) + aoff + m * 2048 + k * 1024); } while (0)
; #define PG8_LDB(dst, b, h) do { _Pragma("unroll") for (int n = 0; n < 2; ++n) _Pragma("unroll") for (int k = 0; k < 2; ++k) dst[n][k] = *(const PG8_LAS bf16x8*)(lds + PG8_SB(b, h) + boff + n * 2048 + k * 1024); } while (0)
; #define PG8_MMA(ai, bj, At, Bt) do { __builtin_amdgcn_s_setprio(1); _Pragma("unroll") for (int m = 0; m < 4; ++m) _Pragma("unroll") for (int n = 0; n < 2; ++n) _Pragma("unroll") for (int k = 0; k < 2; ++k) \
;         acc[ai][bj][m][n] = __builtin_amdgcn_mfma_f32_16x16x32_bf16(Bt[n][k], At[m][k], acc[ai][bj][m][n], 0, 0, 0); __builtin_amdgcn_s_setprio(0); } while (0)
; #define PG8_WAIT_V(n) asm volatile("s_waitcnt vmcnt(" #n ")" ::: "memory")
; template <class Epi, class Sched, bool ALIGN_EPI = false, bool SP2 = false>
; __device__ __forceinline__ void gemm_phase(PG8_LAS unsigned char* lds, const Gemm g, const Sched& S, const Epi& E) {
;     ...
;             const bool last = (t == nt - 2);
;             const char* a1 = cA + (size_t)(t + 1) * kstep;
;             const char* a2 = last ? nA : cA + (size_t)(t + 2) * kstep; const char* b2 = last ? nB : cB + (size_t)(t + 2) * kstep;
;             const char* a3 = a2 + kstep; const char* b3 = b2 + kstep;
;             if (last && has_next) S.a_ready(nxt);
;             if constexpr (SP2) {
;             PG8_LDB(B0, 0, 0); PG8_LDB(B1, 0, 1); PG8_SCHED; PG8_LDA(At, 0, 0); PG8_STAGE(PG8_SA(1, 1), a1 + hstep, voffA);
;             PG8_WAIT_V(8); PG8_WAIT_L(0); PG8_BAR; PG8_MMA(0, 0, At, B0); PG8_MMA(0, 1, At, B1); PG8_BAR; PG8_SCHED;
;             PG8_LDA(At, 0, 1); PG8_STAGE(PG8_SB(0, 0), b2, voffB); PG8_STAGE(PG8_SB(0, 1), b2 + hstep, voffB); PG8_STAGE(PG8_SA(0, 0), a2, voffA);
;             PG8_WAIT_V(8); PG8_WAIT_L(0); PG8_BAR; PG8_MMA(1, 0, At, B0); PG8_MMA(1, 1, At, B1); PG8_BAR; PG8_SCHED;
.LBB0_232:
	s_add_u32 s2, s0, 0x100
	s_addc_u32 s3, s1, 0
	s_cmp_eq_u32 s30, 28
	s_cselect_b32 s10, s25, s2
	s_cselect_b32 s11, s24, s3
	s_cselect_b32 s8, s27, s28
	s_cselect_b32 s9, s26, s29
	s_add_u32 s6, s10, 0x80
	s_addc_u32 s7, s11, 0
	s_add_i32 s31, 0, 0x10000
	s_add_i32 s33, 0, 0x14000
	ds_read_b128 v[66:69], v244
	ds_read_b128 v[70:73], v244 offset:1024
	ds_read_b128 v[74:77], v244 offset:2048
	ds_read_b128 v[78:81], v244 offset:3072
	ds_read_b128 v[146:149], v244 offset:16384
	ds_read_b128 v[150:153], v244 offset:17408
	ds_read_b128 v[154:157], v244 offset:18432
	ds_read_b128 v[158:161], v244 offset:19456
	s_add_u32 s0, s0, 0x80080
	s_addc_u32 s1, s1, 0
	ds_read_b128 v[178:181], v223
	ds_read_b128 v[182:185], v223 offset:1024
	ds_read_b128 v[192:195], v223 offset:2048
	ds_read_b128 v[196:199], v223 offset:3072
	ds_read_b128 v[200:203], v223 offset:4096
	ds_read_b128 v[204:207], v223 offset:5120
	ds_read_b128 v[208:211], v223 offset:6144
	ds_read_b128 v[212:215], v223 offset:7168
	s_add_i32 m0, s13, 0xc000
	s_nop 0
	global_load_lds_dwordx4 v1, s[0:1]
	s_add_i32 m0, s13, 0xe000
	s_nop 0
	global_load_lds_dwordx4 v191, s[0:1]
	s_waitcnt vmcnt(8)
	s_waitcnt lgkmcnt(0)
	s_barrier
	s_setprio 1
	s_waitcnt lgkmcnt(0)
	v_mfma_f32_16x16x32_bf16 v[142:145], v[66:69], v[178:181], v[142:145]
	v_mfma_f32_16x16x32_bf16 v[142:145], v[70:73], v[182:185], v[142:145]
	v_mfma_f32_16x16x32_bf16 v[138:141], v[74:77], v[178:181], v[138:141]
	v_mfma_f32_16x16x32_bf16 v[138:141], v[78:81], v[182:185], v[138:141]
	v_mfma_f32_16x16x32_bf16 v[62:65], v[146:149], v[178:181], v[62:65]
	v_mfma_f32_16x16x32_bf16 v[62:65], v[150:153], v[182:185], v[62:65]
	v_mfma_f32_16x16x32_bf16 v[58:61], v[154:157], v[178:181], v[58:61]
	v_mfma_f32_16x16x32_bf16 v[58:61], v[158:161], v[182:185], v[58:61]
	v_mfma_f32_16x16x32_bf16 v[134:137], v[66:69], v[192:195], v[134:137]
	v_mfma_f32_16x16x32_bf16 v[134:137], v[70:73], v[196:199], v[134:137]
	v_mfma_f32_16x16x32_bf16 v[130:133], v[74:77], v[192:195], v[130:133]
	v_mfma_f32_16x16x32_bf16 v[130:133], v[78:81], v[196:199], v[130:133]
	v_mfma_f32_16x16x32_bf16 v[54:57], v[146:149], v[192:195], v[54:57]
	v_mfma_f32_16x16x32_bf16 v[54:57], v[150:153], v[196:199], v[54:57]
	v_mfma_f32_16x16x32_bf16 v[50:53], v[154:157], v[192:195], v[50:53]
	v_mfma_f32_16x16x32_bf16 v[50:53], v[158:161], v[196:199], v[50:53]
	v_mfma_f32_16x16x32_bf16 v[126:129], v[66:69], v[200:203], v[126:129]
	v_mfma_f32_16x16x32_bf16 v[126:129], v[70:73], v[204:207], v[126:129]
	v_mfma_f32_16x16x32_bf16 v[122:125], v[74:77], v[200:203], v[122:125]
	v_mfma_f32_16x16x32_bf16 v[122:125], v[78:81], v[204:207], v[122:125]
	v_mfma_f32_16x16x32_bf16 v[46:49], v[146:149], v[200:203], v[46:49]
	v_mfma_f32_16x16x32_bf16 v[46:49], v[150:153], v[204:207], v[46:49]
	v_mfma_f32_16x16x32_bf16 v[42:45], v[154:157], v[200:203], v[42:45]
	v_mfma_f32_16x16x32_bf16 v[42:45], v[158:161], v[204:207], v[42:45]
	v_mfma_f32_16x16x32_bf16 v[118:121], v[66:69], v[208:211], v[118:121]
	v_mfma_f32_16x16x32_bf16 v[118:121], v[70:73], v[212:215], v[118:121]
	v_mfma_f32_16x16x32_bf16 v[114:117], v[74:77], v[208:211], v[114:117]
	v_mfma_f32_16x16x32_bf16 v[114:117], v[78:81], v[212:215], v[114:117]
	v_mfma_f32_16x16x32_bf16 v[38:41], v[146:149], v[208:211], v[38:41]
	v_mfma_f32_16x16x32_bf16 v[38:41], v[150:153], v[212:215], v[38:41]
	v_mfma_f32_16x16x32_bf16 v[34:37], v[154:157], v[208:211], v[34:37]
	v_mfma_f32_16x16x32_bf16 v[34:37], v[158:161], v[212:215], v[34:37]
	s_setprio 0
	s_barrier
	s_mov_b64 s[0:1], s[8:9]
	s_add_i32 s31, s31, s12
	ds_read_b128 v[178:181], v223 offset:16384
	ds_read_b128 v[182:185], v223 offset:17408
	ds_read_b128 v[192:195], v223 offset:18432
	ds_read_b128 v[196:199], v223 offset:19456
	ds_read_b128 v[200:203], v223 offset:20480
	ds_read_b128 v[204:207], v223 offset:21504
	ds_read_b128 v[208:211], v223 offset:22528
	ds_read_b128 v[212:215], v223 offset:23552
	s_mov_b32 m0, s31
	s_nop 0
	global_load_lds_dwordx4 v189, s[0:1]
	s_add_i32 m0, s31, 0x2000
	s_nop 0
	global_load_lds_dwordx4 v219, s[0:1]
	s_add_u32 s0, s8, 0x80000
	s_addc_u32 s1, s9, 0
	s_add_i32 s31, s33, s12
	s_mov_b32 m0, s31
	s_nop 0
	global_load_lds_dwordx4 v189, s[0:1]
	s_add_i32 m0, s31, 0x2000
	s_nop 0
	global_load_lds_dwordx4 v219, s[0:1]
	s_mov_b64 s[0:1], s[10:11]
	s_mov_b32 m0, s13
	s_nop 0
	global_load_lds_dwordx4 v1, s[0:1]
	s_mov_b32 m0, s14
	s_nop 0
	global_load_lds_dwordx4 v191, s[0:1]
	s_waitcnt vmcnt(8)
	s_waitcnt lgkmcnt(0)
	s_barrier
	s_setprio 1
	s_waitcnt lgkmcnt(0)
	v_mfma_f32_16x16x32_bf16 v[110:113], v[66:69], v[178:181], v[110:113]
	v_mfma_f32_16x16x32_bf16 v[110:113], v[70:73], v[182:185], v[110:113]
	v_mfma_f32_16x16x32_bf16 v[106:109], v[74:77], v[178:181], v[106:109]
	v_mfma_f32_16x16x32_bf16 v[106:109], v[78:81], v[182:185], v[106:109]
	v_mfma_f32_16x16x32_bf16 v[30:33], v[146:149], v[178:181], v[30:33]
	v_mfma_f32_16x16x32_bf16 v[30:33], v[150:153], v[182:185], v[30:33]
	v_mfma_f32_16x16x32_bf16 v[26:29], v[154:157], v[178:181], v[26:29]
	v_mfma_f32_16x16x32_bf16 v[26:29], v[158:161], v[182:185], v[26:29]
	v_mfma_f32_16x16x32_bf16 v[102:105], v[66:69], v[192:195], v[102:105]
	v_mfma_f32_16x16x32_bf16 v[102:105], v[70:73], v[196:199], v[102:105]
	v_mfma_f32_16x16x32_bf16 v[98:101], v[74:77], v[192:195], v[98:101]
	v_mfma_f32_16x16x32_bf16 v[98:101], v[78:81], v[196:199], v[98:101]
	v_mfma_f32_16x16x32_bf16 v[22:25], v[146:149], v[192:195], v[22:25]
	v_mfma_f32_16x16x32_bf16 v[22:25], v[150:153], v[196:199], v[22:25]
	v_mfma_f32_16x16x32_bf16 v[18:21], v[154:157], v[192:195], v[18:21]
	v_mfma_f32_16x16x32_bf16 v[18:21], v[158:161], v[196:199], v[18:21]
	v_mfma_f32_16x16x32_bf16 v[94:97], v[66:69], v[200:203], v[94:97]
	v_mfma_f32_16x16x32_bf16 v[94:97], v[70:73], v[204:207], v[94:97]
	v_mfma_f32_16x16x32_bf16 v[90:93], v[74:77], v[200:203], v[90:93]
	v_mfma_f32_16x16x32_bf16 v[90:93], v[78:81], v[204:207], v[90:93]
	v_mfma_f32_16x16x32_bf16 v[14:17], v[146:149], v[200:203], v[14:17]
	v_mfma_f32_16x16x32_bf16 v[14:17], v[150:153], v[204:207], v[14:17]
	v_mfma_f32_16x16x32_bf16 v[10:13], v[154:157], v[200:203], v[10:13]
	v_mfma_f32_16x16x32_bf16 v[10:13], v[158:161], v[204:207], v[10:13]
	v_mfma_f32_16x16x32_bf16 v[66:69], v[66:69], v[208:211], v[86:89]
	v_mfma_f32_16x16x32_bf16 v[66:69], v[70:73], v[212:215], v[66:69]
	v_mfma_f32_16x16x32_bf16 v[70:73], v[74:77], v[208:211], v[82:85]
	v_mfma_f32_16x16x32_bf16 v[70:73], v[78:81], v[212:215], v[70:73]
	v_mfma_f32_16x16x32_bf16 v[6:9], v[146:149], v[208:211], v[6:9]
	v_mfma_f32_16x16x32_bf16 v[6:9], v[150:153], v[212:215], v[6:9]
	v_mfma_f32_16x16x32_bf16 v[2:5], v[154:157], v[208:211], v[2:5]
	v_mfma_f32_16x16x32_bf16 v[2:5], v[158:161], v[212:215], v[2:5]
	s_setprio 0
	s_barrier
; #define PG8_STAGE(bufoff, gbase, voff) do { const char* gb_ = (const char*)(gbase); asm volatile("" : "+s"(gb_)); _Pragma("unroll") for (int _i = 0; _i < 2; ++_i) { unsigned vo_ = (voff)[_i]; asm volatile("" : "+v"(vo_));        \
;         __builtin_amdgcn_global_load_lds((const unsigned*)(gb_ + vo_), (PG8_LAS unsigned*)(lds + (bufoff) + ldsw + _i * 8192), 16, 0, 0); } } while (0)
; #define PG8_LDA(dst, b, h) do { _Pragma("unroll") for (int m = 0; m < 4; ++m) _Pragma("unroll") for (int k = 0; k < 2; ++k) dst[m][k] = *(const PG8_LAS bf16x8*)(lds + PG8_SA(b, h) + aoff + m * 2048 + k * 1024); } while (0)
; #define PG8_LDB(dst, b, h) do { _Pragma("unroll") for (int n = 0; n < 2; ++n) _Pragma("unroll") for (int k = 0; k < 2; ++k) dst[n][k] = *(const PG8_LAS bf16x8*)(lds + PG8_SB(b, h) + boff + n * 2048 + k * 1024); } while (0)
; #define PG8_MMA(ai, bj, At, Bt) do { __builtin_amdgcn_s_setprio(1); _Pragma("unroll") for (int m = 0; m < 4; ++m) _Pragma("unroll") for (int n = 0; n < 2; ++n) _Pragma("unroll") for (int k = 0; k < 2; ++k) \
;         acc[ai][bj][m][n] = __builtin_amdgcn_mfma_f32_16x16x32_bf16(Bt[n][k], At[m][k], acc[ai][bj][m][n], 0, 0, 0); __builtin_amdgcn_s_setprio(0); } while (0)
; #define PG8_WAIT_V(n) asm volatile("s_waitcnt vmcnt(" #n ")" ::: "memory")
; #define PG8_WAIT_L(n) asm volatile("s_waitcnt lgkmcnt(" #n ")" ::: "memory")
; #define PG8_BAR __builtin_amdgcn_s_barrier()
; #define PG8_SCHED __builtin_amdgcn_sched_barrier(0)
; template <class Epi, class Sched, bool ALIGN_EPI = false, bool SP2 = false>
; __device__ __forceinline__ void gemm_phase(PG8_LAS unsigned char* lds, const Gemm g, const Sched& S, const Epi& E) {
;     ...
;             PG8_LDB(B0, 1, 0); PG8_LDB(B1, 1, 1); PG8_SCHED; PG8_LDA(At, 1, 0); PG8_STAGE(PG8_SA(0, 1), a2 + hstep, voffA);
;             PG8_WAIT_V(8); PG8_WAIT_L(0); PG8_BAR; PG8_MMA(0, 0, At, B0); PG8_MMA(0, 1, At, B1); PG8_BAR; PG8_SCHED;
;             PG8_LDA(At, 1, 1); PG8_STAGE(PG8_SB(1, 0), b3, voffB); PG8_STAGE(PG8_SB(1, 1), b3 + hstep, voffB); PG8_STAGE(PG8_SA(1, 0), a3, voffA);
;             PG8_WAIT_V(8); PG8_WAIT_L(0); PG8_BAR; PG8_MMA(1, 0, At, B0); PG8_MMA(1, 1, At, B1); PG8_BAR; PG8_SCHED;
;     ...
;         if constexpr (ALIGN_EPI) { if (wr == 0) PG8_BAR; }
	s_add_i32 s31, 0, 0x18000
	s_add_i32 s33, 0, 0x1c000
	ds_read_b128 v[74:77], v244 offset:32768
	ds_read_b128 v[78:81], v244 offset:33792
	ds_read_b128 v[82:85], v244 offset:34816
	ds_read_b128 v[146:149], v244 offset:35840
	ds_read_b128 v[150:153], v244 offset:49152
	ds_read_b128 v[154:157], v244 offset:50176
	ds_read_b128 v[158:161], v244 offset:51200
	ds_read_b128 v[178:181], v244 offset:52224
	s_add_u32 s0, s10, 0x80000
	s_addc_u32 s1, s11, 0
	s_mov_b32 m0, s15
	ds_read_b128 v[86:89], v223 offset:32768
	ds_read_b128 v[182:185], v223 offset:33792
	ds_read_b128 v[192:195], v223 offset:34816
	ds_read_b128 v[196:199], v223 offset:35840
	ds_read_b128 v[200:203], v223 offset:36864
	ds_read_b128 v[204:207], v223 offset:37888
	ds_read_b128 v[208:211], v223 offset:38912
	ds_read_b128 v[212:215], v223 offset:39936
	s_nop 0
	global_load_lds_dwordx4 v1, s[0:1]
	s_mov_b32 m0, s16
	s_nop 0
	global_load_lds_dwordx4 v191, s[0:1]
	s_waitcnt vmcnt(8)
	s_waitcnt lgkmcnt(0)
	s_barrier
	s_setprio 1
	s_waitcnt lgkmcnt(0)
	v_mfma_f32_16x16x32_bf16 v[142:145], v[74:77], v[86:89], v[142:145]
	v_mfma_f32_16x16x32_bf16 v[142:145], v[78:81], v[182:185], v[142:145]
	v_mfma_f32_16x16x32_bf16 v[138:141], v[82:85], v[86:89], v[138:141]
	v_mfma_f32_16x16x32_bf16 v[138:141], v[146:149], v[182:185], v[138:141]
	v_mfma_f32_16x16x32_bf16 v[62:65], v[150:153], v[86:89], v[62:65]
	v_mfma_f32_16x16x32_bf16 v[62:65], v[154:157], v[182:185], v[62:65]
	v_mfma_f32_16x16x32_bf16 v[58:61], v[158:161], v[86:89], v[58:61]
	v_mfma_f32_16x16x32_bf16 v[58:61], v[178:181], v[182:185], v[58:61]
	v_mfma_f32_16x16x32_bf16 v[134:137], v[74:77], v[192:195], v[134:137]
	v_mfma_f32_16x16x32_bf16 v[134:137], v[78:81], v[196:199], v[134:137]
	v_mfma_f32_16x16x32_bf16 v[130:133], v[82:85], v[192:195], v[130:133]
	v_mfma_f32_16x16x32_bf16 v[130:133], v[146:149], v[196:199], v[130:133]
	v_mfma_f32_16x16x32_bf16 v[54:57], v[150:153], v[192:195], v[54:57]
	v_mfma_f32_16x16x32_bf16 v[54:57], v[154:157], v[196:199], v[54:57]
	v_mfma_f32_16x16x32_bf16 v[50:53], v[158:161], v[192:195], v[50:53]
	v_mfma_f32_16x16x32_bf16 v[50:53], v[178:181], v[196:199], v[50:53]
	v_mfma_f32_16x16x32_bf16 v[126:129], v[74:77], v[200:203], v[126:129]
	v_mfma_f32_16x16x32_bf16 v[126:129], v[78:81], v[204:207], v[126:129]
	v_mfma_f32_16x16x32_bf16 v[122:125], v[82:85], v[200:203], v[122:125]
	v_mfma_f32_16x16x32_bf16 v[122:125], v[146:149], v[204:207], v[122:125]
	v_mfma_f32_16x16x32_bf16 v[46:49], v[150:153], v[200:203], v[46:49]
	v_mfma_f32_16x16x32_bf16 v[46:49], v[154:157], v[204:207], v[46:49]
	v_mfma_f32_16x16x32_bf16 v[42:45], v[158:161], v[200:203], v[42:45]
	v_mfma_f32_16x16x32_bf16 v[42:45], v[178:181], v[204:207], v[42:45]
	v_mfma_f32_16x16x32_bf16 v[118:121], v[74:77], v[208:211], v[118:121]
	v_mfma_f32_16x16x32_bf16 v[118:121], v[78:81], v[212:215], v[118:121]
	v_mfma_f32_16x16x32_bf16 v[114:117], v[82:85], v[208:211], v[114:117]
	v_mfma_f32_16x16x32_bf16 v[114:117], v[146:149], v[212:215], v[114:117]
	v_mfma_f32_16x16x32_bf16 v[38:41], v[150:153], v[208:211], v[38:41]
	v_mfma_f32_16x16x32_bf16 v[38:41], v[154:157], v[212:215], v[38:41]
	v_mfma_f32_16x16x32_bf16 v[34:37], v[158:161], v[208:211], v[34:37]
	v_mfma_f32_16x16x32_bf16 v[34:37], v[178:181], v[212:215], v[34:37]
	s_setprio 0
	s_barrier
	s_add_u32 s0, s8, 0x80
	s_addc_u32 s1, s9, 0
	s_add_i32 s10, s31, s12
	ds_read_b128 v[182:185], v223 offset:49152
	ds_read_b128 v[192:195], v223 offset:50176
	ds_read_b128 v[196:199], v223 offset:51200
	ds_read_b128 v[200:203], v223 offset:52224
	ds_read_b128 v[204:207], v223 offset:53248
	ds_read_b128 v[208:211], v223 offset:54272
	ds_read_b128 v[212:215], v223 offset:55296
	ds_read_b128 v[224:227], v223 offset:56320
	s_mov_b32 m0, s10
	s_nop 0
	global_load_lds_dwordx4 v189, s[0:1]
	s_add_i32 m0, s10, 0x2000
	s_nop 0
	global_load_lds_dwordx4 v219, s[0:1]
	s_add_u32 s0, s8, 0x80080
	s_addc_u32 s1, s9, 0
	s_add_i32 s8, s33, s12
	s_mov_b32 m0, s8
	s_nop 0
	global_load_lds_dwordx4 v189, s[0:1]
	s_add_i32 m0, s8, 0x2000
	s_nop 0
	global_load_lds_dwordx4 v219, s[0:1]
	s_mov_b32 m0, s19
	s_nop 0
	global_load_lds_dwordx4 v1, s[6:7]
	s_mov_b32 m0, s20
	s_nop 0
	global_load_lds_dwordx4 v191, s[6:7]
	s_waitcnt vmcnt(8)
	s_waitcnt lgkmcnt(0)
	s_barrier
	s_setprio 1
	s_waitcnt lgkmcnt(0)
	v_mfma_f32_16x16x32_bf16 v[86:89], v[74:77], v[182:185], v[110:113]
	v_mfma_f32_16x16x32_bf16 v[110:113], v[78:81], v[192:195], v[86:89]
	v_mfma_f32_16x16x32_bf16 v[86:89], v[82:85], v[182:185], v[106:109]
	v_mfma_f32_16x16x32_bf16 v[106:109], v[146:149], v[192:195], v[86:89]
	v_mfma_f32_16x16x32_bf16 v[30:33], v[150:153], v[182:185], v[30:33]
	v_mfma_f32_16x16x32_bf16 v[30:33], v[154:157], v[192:195], v[30:33]
	v_mfma_f32_16x16x32_bf16 v[26:29], v[158:161], v[182:185], v[26:29]
	v_mfma_f32_16x16x32_bf16 v[26:29], v[178:181], v[192:195], v[26:29]
	v_mfma_f32_16x16x32_bf16 v[86:89], v[74:77], v[196:199], v[102:105]
	v_mfma_f32_16x16x32_bf16 v[102:105], v[78:81], v[200:203], v[86:89]
	v_mfma_f32_16x16x32_bf16 v[86:89], v[82:85], v[196:199], v[98:101]
	v_mfma_f32_16x16x32_bf16 v[98:101], v[146:149], v[200:203], v[86:89]
	v_mfma_f32_16x16x32_bf16 v[22:25], v[150:153], v[196:199], v[22:25]
	v_mfma_f32_16x16x32_bf16 v[22:25], v[154:157], v[200:203], v[22:25]
	v_mfma_f32_16x16x32_bf16 v[18:21], v[158:161], v[196:199], v[18:21]
	v_mfma_f32_16x16x32_bf16 v[18:21], v[178:181], v[200:203], v[18:21]
	v_mfma_f32_16x16x32_bf16 v[86:89], v[74:77], v[204:207], v[94:97]
	v_mfma_f32_16x16x32_bf16 v[94:97], v[78:81], v[208:211], v[86:89]
	v_mfma_f32_16x16x32_bf16 v[86:89], v[82:85], v[204:207], v[90:93]
	v_mfma_f32_16x16x32_bf16 v[90:93], v[146:149], v[208:211], v[86:89]
	v_mfma_f32_16x16x32_bf16 v[14:17], v[150:153], v[204:207], v[14:17]
	v_mfma_f32_16x16x32_bf16 v[14:17], v[154:157], v[208:211], v[14:17]
	v_mfma_f32_16x16x32_bf16 v[10:13], v[158:161], v[204:207], v[10:13]
	v_mfma_f32_16x16x32_bf16 v[10:13], v[178:181], v[208:211], v[10:13]
	v_mfma_f32_16x16x32_bf16 v[66:69], v[74:77], v[212:215], v[66:69]
	v_mfma_f32_16x16x32_bf16 v[86:89], v[78:81], v[224:227], v[66:69]
	v_mfma_f32_16x16x32_bf16 v[66:69], v[82:85], v[212:215], v[70:73]
	v_mfma_f32_16x16x32_bf16 v[82:85], v[146:149], v[224:227], v[66:69]
	v_mfma_f32_16x16x32_bf16 v[6:9], v[150:153], v[212:215], v[6:9]
	v_mfma_f32_16x16x32_bf16 v[6:9], v[154:157], v[224:227], v[6:9]
	v_mfma_f32_16x16x32_bf16 v[2:5], v[158:161], v[212:215], v[2:5]
	v_mfma_f32_16x16x32_bf16 v[2:5], v[178:181], v[224:227], v[2:5]
	s_setprio 0
	s_barrier
	s_add_i32 s30, s30, 2
	s_add_u32 s28, s28, 0x100
	s_addc_u32 s29, s29, 0
	s_cmp_gt_u32 s30, 29
	s_mov_b64 s[0:1], s[2:3]
	s_cbranch_scc0 .LBB0_232
	s_and_b64 vcc, exec, s[44:45]
	s_cbranch_vccz .LBB0_235
	s_barrier

; #define PG8_STAGE(bufoff, gbase, voff) do { const char* gb_ = (const char*)(gbase); asm volatile("" : "+s"(gb_)); _Pragma("unroll") for (int _i = 0; _i < 2; ++_i) { unsigned vo_ = (voff)[_i]; asm volatile("" : "+v"(vo_));        \
;         __builtin_amdgcn_global_load_lds((const unsigned*)(gb_ + vo_), (PG8_LAS unsigned*)(lds + (bufoff) + ldsw + _i * 8192), 16, 0, 0); } } while (0)
; #define PG8_LDA(dst, b, h) do { _Pragma("unroll") for (int m = 0; m < 4; ++m) _Pragma("unroll") for (int k = 0; k < 2; ++k) dst[m][k] = *(const PG8_LAS bf16x8*)(lds + PG8_SA(b, h) + aoff + m * 2048 + k * 1024); } while (0)
; #define PG8_LDB(dst, b, h) do { _Pragma("unroll") for (int n = 0; n < 2; ++n) _Pragma("unroll") for (int k = 0; k < 2; ++k) dst[n][k] = *(const PG8_LAS bf16x8*)(lds + PG8_SB(b, h) + boff + n * 2048 + k * 1024); } while (0)
; #define PG8_MMA(ai, bj, At, Bt) do { __builtin_amdgcn_s_setprio(1); _Pragma("unroll") for (int m = 0; m < 4; ++m) _Pragma("unroll") for (int n = 0; n < 2; ++n) _Pragma("unroll") for (int k = 0; k < 2; ++k) \
;         acc[ai][bj][m][n] = __builtin_amdgcn_mfma_f32_16x16x32_bf16(Bt[n][k], At[m][k], acc[ai][bj][m][n], 0, 0, 0); __builtin_amdgcn_s_setprio(0); } while (0)
; #define PG8_WAIT_V(n) asm volatile("s_waitcnt vmcnt(" #n ")" ::: "memory")
; template <class Epi, class Sched, bool ALIGN_EPI = false, bool SP2 = false>
; __device__ __forceinline__ void gemm_phase(PG8_LAS unsigned char* lds, const Gemm g, const Sched& S, const Epi& E) {
;     ...
;             const bool last = (t == nt - 2);
;             const char* a1 = cA + (size_t)(t + 1) * kstep;
;             const char* a2 = last ? nA : cA + (size_t)(t + 2) * kstep; const char* b2 = last ? nB : cB + (size_t)(t + 2) * kstep;
;             const char* a3 = a2 + kstep; const char* b3 = b2 + kstep;
;             if (last && has_next) S.a_ready(nxt);
;             if constexpr (SP2) {
;             PG8_LDB(B0, 0, 0); PG8_LDB(B1, 0, 1); PG8_SCHED; PG8_LDA(At, 0, 0); PG8_STAGE(PG8_SA(1, 1), a1 + hstep, voffA);
;             PG8_WAIT_V(8); PG8_WAIT_L(0); PG8_BAR; PG8_MMA(0, 0, At, B0); PG8_MMA(0, 1, At, B1); PG8_BAR; PG8_SCHED;
;             PG8_LDA(At, 0, 1); PG8_STAGE(PG8_SB(0, 0), b2, voffB); PG8_STAGE(PG8_SB(0, 1), b2 + hstep, voffB); PG8_STAGE(PG8_SA(0, 0), a2, voffA);
;             PG8_WAIT_V(8); PG8_WAIT_L(0); PG8_BAR; PG8_MMA(1, 0, At, B0); PG8_MMA(1, 1, At, B1); PG8_BAR; PG8_SCHED;
.LBB0_555:
	s_add_u32 s6, s4, 0x100
	s_addc_u32 s7, s5, 0
	s_cmp_eq_u32 s51, 28
	s_cselect_b32 s12, s35, s6
	s_cselect_b32 s13, s34, s7
	s_cselect_b32 s10, s39, s40
	s_cselect_b32 s11, s38, s49
	s_add_u32 s8, s12, 0x80
	s_addc_u32 s9, s13, 0
	s_add_i32 s56, 0, 0x10000
	s_add_i32 s57, 0, 0x14000
	ds_read_b128 v[26:29], v244
	ds_read_b128 v[30:33], v244 offset:1024
	ds_read_b128 v[98:101], v244 offset:2048
	ds_read_b128 v[102:105], v244 offset:3072
	ds_read_b128 v[146:149], v244 offset:16384
	ds_read_b128 v[150:153], v244 offset:17408
	ds_read_b128 v[154:157], v244 offset:18432
	ds_read_b128 v[158:161], v244 offset:19456
	s_add_u32 s4, s4, 0x80080
	s_addc_u32 s5, s5, 0
	ds_read_b128 v[178:181], v210
	ds_read_b128 v[182:185], v210 offset:1024
	ds_read_b128 v[186:189], v210 offset:2048
	ds_read_b128 v[190:193], v210 offset:3072
	ds_read_b128 v[194:197], v210 offset:4096
	ds_read_b128 v[198:201], v210 offset:5120
	ds_read_b128 v[202:205], v210 offset:6144
	ds_read_b128 v[212:215], v210 offset:7168
	s_add_i32 m0, s18, 0xc000
	s_nop 0
	global_load_lds_dwordx4 v1, s[4:5]
	s_add_i32 m0, s18, 0xe000
	s_nop 0
	global_load_lds_dwordx4 v164, s[4:5]
	s_waitcnt vmcnt(8)
	s_waitcnt lgkmcnt(0)
	s_barrier
	s_setprio 1
	s_waitcnt lgkmcnt(0)
	v_mfma_f32_16x16x32_bf16 v[142:145], v[26:29], v[178:181], v[142:145]
	v_mfma_f32_16x16x32_bf16 v[142:145], v[30:33], v[182:185], v[142:145]
	v_mfma_f32_16x16x32_bf16 v[138:141], v[98:101], v[178:181], v[138:141]
	v_mfma_f32_16x16x32_bf16 v[138:141], v[102:105], v[182:185], v[138:141]
	v_mfma_f32_16x16x32_bf16 v[70:73], v[146:149], v[178:181], v[70:73]
	v_mfma_f32_16x16x32_bf16 v[70:73], v[150:153], v[182:185], v[70:73]
	v_mfma_f32_16x16x32_bf16 v[66:69], v[154:157], v[178:181], v[66:69]
	v_mfma_f32_16x16x32_bf16 v[66:69], v[158:161], v[182:185], v[66:69]
	v_mfma_f32_16x16x32_bf16 v[134:137], v[26:29], v[186:189], v[134:137]
	v_mfma_f32_16x16x32_bf16 v[134:137], v[30:33], v[190:193], v[134:137]
	v_mfma_f32_16x16x32_bf16 v[130:133], v[98:101], v[186:189], v[130:133]
	v_mfma_f32_16x16x32_bf16 v[130:133], v[102:105], v[190:193], v[130:133]
	v_mfma_f32_16x16x32_bf16 v[62:65], v[146:149], v[186:189], v[62:65]
	v_mfma_f32_16x16x32_bf16 v[62:65], v[150:153], v[190:193], v[62:65]
	v_mfma_f32_16x16x32_bf16 v[58:61], v[154:157], v[186:189], v[58:61]
	v_mfma_f32_16x16x32_bf16 v[58:61], v[158:161], v[190:193], v[58:61]
	v_mfma_f32_16x16x32_bf16 v[126:129], v[26:29], v[194:197], v[126:129]
	v_mfma_f32_16x16x32_bf16 v[126:129], v[30:33], v[198:201], v[126:129]
	v_mfma_f32_16x16x32_bf16 v[122:125], v[98:101], v[194:197], v[122:125]
	v_mfma_f32_16x16x32_bf16 v[122:125], v[102:105], v[198:201], v[122:125]
	v_mfma_f32_16x16x32_bf16 v[54:57], v[146:149], v[194:197], v[54:57]
	v_mfma_f32_16x16x32_bf16 v[54:57], v[150:153], v[198:201], v[54:57]
	v_mfma_f32_16x16x32_bf16 v[50:53], v[154:157], v[194:197], v[50:53]
	v_mfma_f32_16x16x32_bf16 v[50:53], v[158:161], v[198:201], v[50:53]
	v_mfma_f32_16x16x32_bf16 v[118:121], v[26:29], v[202:205], v[118:121]
	v_mfma_f32_16x16x32_bf16 v[118:121], v[30:33], v[212:215], v[118:121]
	v_mfma_f32_16x16x32_bf16 v[114:117], v[98:101], v[202:205], v[114:117]
	v_mfma_f32_16x16x32_bf16 v[114:117], v[102:105], v[212:215], v[114:117]
	v_mfma_f32_16x16x32_bf16 v[46:49], v[146:149], v[202:205], v[46:49]
	v_mfma_f32_16x16x32_bf16 v[46:49], v[150:153], v[212:215], v[46:49]
	v_mfma_f32_16x16x32_bf16 v[42:45], v[154:157], v[202:205], v[42:45]
	v_mfma_f32_16x16x32_bf16 v[42:45], v[158:161], v[212:215], v[42:45]
	s_setprio 0
	s_barrier
	s_mov_b64 s[4:5], s[10:11]
	s_add_i32 s56, s56, s17
	ds_read_b128 v[178:181], v210 offset:16384
	ds_read_b128 v[182:185], v210 offset:17408
	ds_read_b128 v[186:189], v210 offset:18432
	ds_read_b128 v[190:193], v210 offset:19456
	ds_read_b128 v[194:197], v210 offset:20480
	ds_read_b128 v[198:201], v210 offset:21504
	ds_read_b128 v[202:205], v210 offset:22528
	ds_read_b128 v[212:215], v210 offset:23552
	s_mov_b32 m0, s56
	s_nop 0
	global_load_lds_dwordx4 v162, s[4:5]
	s_add_i32 m0, s56, 0x2000
	s_nop 0
	global_load_lds_dwordx4 v206, s[4:5]
	s_add_u32 s4, s10, 0x80000
	s_addc_u32 s5, s11, 0
	s_add_i32 s56, s57, s17
	s_mov_b32 m0, s56
	s_nop 0
	global_load_lds_dwordx4 v162, s[4:5]
	s_add_i32 m0, s56, 0x2000
	s_nop 0
	global_load_lds_dwordx4 v206, s[4:5]
	s_mov_b64 s[4:5], s[12:13]
	s_mov_b32 m0, s18
	s_nop 0
	global_load_lds_dwordx4 v1, s[4:5]
	s_mov_b32 m0, s19
	s_nop 0
	global_load_lds_dwordx4 v164, s[4:5]
	s_waitcnt vmcnt(8)
	s_waitcnt lgkmcnt(0)
	s_barrier
	s_setprio 1
	s_waitcnt lgkmcnt(0)
	v_mfma_f32_16x16x32_bf16 v[110:113], v[26:29], v[178:181], v[110:113]
	v_mfma_f32_16x16x32_bf16 v[110:113], v[30:33], v[182:185], v[110:113]
	v_mfma_f32_16x16x32_bf16 v[106:109], v[98:101], v[178:181], v[106:109]
	v_mfma_f32_16x16x32_bf16 v[106:109], v[102:105], v[182:185], v[106:109]
	v_mfma_f32_16x16x32_bf16 v[38:41], v[146:149], v[178:181], v[38:41]
	v_mfma_f32_16x16x32_bf16 v[38:41], v[150:153], v[182:185], v[38:41]
	v_mfma_f32_16x16x32_bf16 v[34:37], v[154:157], v[178:181], v[34:37]
	v_mfma_f32_16x16x32_bf16 v[34:37], v[158:161], v[182:185], v[34:37]
	v_mfma_f32_16x16x32_bf16 v[94:97], v[26:29], v[186:189], v[94:97]
	v_mfma_f32_16x16x32_bf16 v[94:97], v[30:33], v[190:193], v[94:97]
	v_mfma_f32_16x16x32_bf16 v[90:93], v[98:101], v[186:189], v[90:93]
	v_mfma_f32_16x16x32_bf16 v[90:93], v[102:105], v[190:193], v[90:93]
	v_mfma_f32_16x16x32_bf16 v[22:25], v[146:149], v[186:189], v[22:25]
	v_mfma_f32_16x16x32_bf16 v[22:25], v[150:153], v[190:193], v[22:25]
	v_mfma_f32_16x16x32_bf16 v[18:21], v[154:157], v[186:189], v[18:21]
	v_mfma_f32_16x16x32_bf16 v[18:21], v[158:161], v[190:193], v[18:21]
	v_mfma_f32_16x16x32_bf16 v[86:89], v[26:29], v[194:197], v[86:89]
	v_mfma_f32_16x16x32_bf16 v[86:89], v[30:33], v[198:201], v[86:89]
	v_mfma_f32_16x16x32_bf16 v[82:85], v[98:101], v[194:197], v[82:85]
	v_mfma_f32_16x16x32_bf16 v[82:85], v[102:105], v[198:201], v[82:85]
	v_mfma_f32_16x16x32_bf16 v[14:17], v[146:149], v[194:197], v[14:17]
	v_mfma_f32_16x16x32_bf16 v[14:17], v[150:153], v[198:201], v[14:17]
	v_mfma_f32_16x16x32_bf16 v[10:13], v[154:157], v[194:197], v[10:13]
	v_mfma_f32_16x16x32_bf16 v[10:13], v[158:161], v[198:201], v[10:13]
	v_mfma_f32_16x16x32_bf16 v[26:29], v[26:29], v[202:205], v[78:81]
	v_mfma_f32_16x16x32_bf16 v[26:29], v[30:33], v[212:215], v[26:29]
	v_mfma_f32_16x16x32_bf16 v[30:33], v[98:101], v[202:205], v[74:77]
	v_mfma_f32_16x16x32_bf16 v[30:33], v[102:105], v[212:215], v[30:33]
	v_mfma_f32_16x16x32_bf16 v[6:9], v[146:149], v[202:205], v[6:9]
	v_mfma_f32_16x16x32_bf16 v[6:9], v[150:153], v[212:215], v[6:9]
	v_mfma_f32_16x16x32_bf16 v[2:5], v[154:157], v[202:205], v[2:5]
	v_mfma_f32_16x16x32_bf16 v[2:5], v[158:161], v[212:215], v[2:5]
	s_setprio 0
	s_barrier
; #define PG8_STAGE(bufoff, gbase, voff) do { const char* gb_ = (const char*)(gbase); asm volatile("" : "+s"(gb_)); _Pragma("unroll") for (int _i = 0; _i < 2; ++_i) { unsigned vo_ = (voff)[_i]; asm volatile("" : "+v"(vo_));        \
;         __builtin_amdgcn_global_load_lds((const unsigned*)(gb_ + vo_), (PG8_LAS unsigned*)(lds + (bufoff) + ldsw + _i * 8192), 16, 0, 0); } } while (0)
; #define PG8_LDA(dst, b, h) do { _Pragma("unroll") for (int m = 0; m < 4; ++m) _Pragma("unroll") for (int k = 0; k < 2; ++k) dst[m][k] = *(const PG8_LAS bf16x8*)(lds + PG8_SA(b, h) + aoff + m * 2048 + k * 1024); } while (0)
; #define PG8_LDB(dst, b, h) do { _Pragma("unroll") for (int n = 0; n < 2; ++n) _Pragma("unroll") for (int k = 0; k < 2; ++k) dst[n][k] = *(const PG8_LAS bf16x8*)(lds + PG8_SB(b, h) + boff + n * 2048 + k * 1024); } while (0)
; #define PG8_MMA(ai, bj, At, Bt) do { __builtin_amdgcn_s_setprio(1); _Pragma("unroll") for (int m = 0; m < 4; ++m) _Pragma("unroll") for (int n = 0; n < 2; ++n) _Pragma("unroll") for (int k = 0; k < 2; ++k) \
;         acc[ai][bj][m][n] = __builtin_amdgcn_mfma_f32_16x16x32_bf16(Bt[n][k], At[m][k], acc[ai][bj][m][n], 0, 0, 0); __builtin_amdgcn_s_setprio(0); } while (0)
; #define PG8_WAIT_V(n) asm volatile("s_waitcnt vmcnt(" #n ")" ::: "memory")
; #define PG8_WAIT_L(n) asm volatile("s_waitcnt lgkmcnt(" #n ")" ::: "memory")
; #define PG8_BAR __builtin_amdgcn_s_barrier()
; #define PG8_SCHED __builtin_amdgcn_sched_barrier(0)
; template <class Epi, class Sched, bool ALIGN_EPI = false, bool SP2 = false>
; __device__ __forceinline__ void gemm_phase(PG8_LAS unsigned char* lds, const Gemm g, const Sched& S, const Epi& E) {
;     ...
;             PG8_LDB(B0, 1, 0); PG8_LDB(B1, 1, 1); PG8_SCHED; PG8_LDA(At, 1, 0); PG8_STAGE(PG8_SA(0, 1), a2 + hstep, voffA);
;             PG8_WAIT_V(8); PG8_WAIT_L(0); PG8_BAR; PG8_MMA(0, 0, At, B0); PG8_MMA(0, 1, At, B1); PG8_BAR; PG8_SCHED;
;             PG8_LDA(At, 1, 1); PG8_STAGE(PG8_SB(1, 0), b3, voffB); PG8_STAGE(PG8_SB(1, 1), b3 + hstep, voffB); PG8_STAGE(PG8_SA(1, 0), a3, voffA);
;             PG8_WAIT_V(8); PG8_WAIT_L(0); PG8_BAR; PG8_MMA(1, 0, At, B0); PG8_MMA(1, 1, At, B1); PG8_BAR; PG8_SCHED;
	s_add_i32 s56, 0, 0x18000
	s_add_i32 s57, 0, 0x1c000
	ds_read_b128 v[74:77], v244 offset:32768
	ds_read_b128 v[78:81], v244 offset:33792
	ds_read_b128 v[98:101], v244 offset:34816
	ds_read_b128 v[102:105], v244 offset:35840
	ds_read_b128 v[146:149], v244 offset:49152
	ds_read_b128 v[150:153], v244 offset:50176
	ds_read_b128 v[154:157], v244 offset:51200
	ds_read_b128 v[158:161], v244 offset:52224
	s_add_u32 s4, s12, 0x80000
	s_addc_u32 s5, s13, 0
	s_mov_b32 m0, s20
	ds_read_b128 v[178:181], v210 offset:32768
	ds_read_b128 v[182:185], v210 offset:33792
	ds_read_b128 v[186:189], v210 offset:34816
	ds_read_b128 v[190:193], v210 offset:35840
	ds_read_b128 v[194:197], v210 offset:36864
	ds_read_b128 v[198:201], v210 offset:37888
	ds_read_b128 v[202:205], v210 offset:38912
	ds_read_b128 v[212:215], v210 offset:39936
	s_nop 0
	global_load_lds_dwordx4 v1, s[4:5]
	s_mov_b32 m0, s21
	s_nop 0
	global_load_lds_dwordx4 v164, s[4:5]
	s_waitcnt vmcnt(8)
	s_waitcnt lgkmcnt(0)
	s_barrier
	s_setprio 1
	s_waitcnt lgkmcnt(0)
	v_mfma_f32_16x16x32_bf16 v[142:145], v[74:77], v[178:181], v[142:145]
	v_mfma_f32_16x16x32_bf16 v[142:145], v[78:81], v[182:185], v[142:145]
	v_mfma_f32_16x16x32_bf16 v[138:141], v[98:101], v[178:181], v[138:141]
	v_mfma_f32_16x16x32_bf16 v[138:141], v[102:105], v[182:185], v[138:141]
	v_mfma_f32_16x16x32_bf16 v[70:73], v[146:149], v[178:181], v[70:73]
	v_mfma_f32_16x16x32_bf16 v[70:73], v[150:153], v[182:185], v[70:73]
	v_mfma_f32_16x16x32_bf16 v[66:69], v[154:157], v[178:181], v[66:69]
	v_mfma_f32_16x16x32_bf16 v[66:69], v[158:161], v[182:185], v[66:69]
	v_mfma_f32_16x16x32_bf16 v[134:137], v[74:77], v[186:189], v[134:137]
	v_mfma_f32_16x16x32_bf16 v[134:137], v[78:81], v[190:193], v[134:137]
	v_mfma_f32_16x16x32_bf16 v[130:133], v[98:101], v[186:189], v[130:133]
	v_mfma_f32_16x16x32_bf16 v[130:133], v[102:105], v[190:193], v[130:133]
	v_mfma_f32_16x16x32_bf16 v[62:65], v[146:149], v[186:189], v[62:65]
	v_mfma_f32_16x16x32_bf16 v[62:65], v[150:153], v[190:193], v[62:65]
	v_mfma_f32_16x16x32_bf16 v[58:61], v[154:157], v[186:189], v[58:61]
	v_mfma_f32_16x16x32_bf16 v[58:61], v[158:161], v[190:193], v[58:61]
	v_mfma_f32_16x16x32_bf16 v[126:129], v[74:77], v[194:197], v[126:129]
	v_mfma_f32_16x16x32_bf16 v[126:129], v[78:81], v[198:201], v[126:129]
	v_mfma_f32_16x16x32_bf16 v[122:125], v[98:101], v[194:197], v[122:125]
	v_mfma_f32_16x16x32_bf16 v[122:125], v[102:105], v[198:201], v[122:125]
	v_mfma_f32_16x16x32_bf16 v[54:57], v[146:149], v[194:197], v[54:57]
	v_mfma_f32_16x16x32_bf16 v[54:57], v[150:153], v[198:201], v[54:57]
	v_mfma_f32_16x16x32_bf16 v[50:53], v[154:157], v[194:197], v[50:53]
	v_mfma_f32_16x16x32_bf16 v[50:53], v[158:161], v[198:201], v[50:53]
	v_mfma_f32_16x16x32_bf16 v[118:121], v[74:77], v[202:205], v[118:121]
	v_mfma_f32_16x16x32_bf16 v[118:121], v[78:81], v[212:215], v[118:121]
	v_mfma_f32_16x16x32_bf16 v[114:117], v[98:101], v[202:205], v[114:117]
	v_mfma_f32_16x16x32_bf16 v[114:117], v[102:105], v[212:215], v[114:117]
	v_mfma_f32_16x16x32_bf16 v[46:49], v[146:149], v[202:205], v[46:49]
	v_mfma_f32_16x16x32_bf16 v[46:49], v[150:153], v[212:215], v[46:49]
	v_mfma_f32_16x16x32_bf16 v[42:45], v[154:157], v[202:205], v[42:45]
	v_mfma_f32_16x16x32_bf16 v[42:45], v[158:161], v[212:215], v[42:45]
	s_setprio 0
	s_barrier
	s_add_u32 s4, s10, 0x80
	s_addc_u32 s5, s11, 0
	s_add_i32 s12, s56, s17
	ds_read_b128 v[178:181], v210 offset:49152
	ds_read_b128 v[182:185], v210 offset:50176
	ds_read_b128 v[186:189], v210 offset:51200
	ds_read_b128 v[190:193], v210 offset:52224
	ds_read_b128 v[194:197], v210 offset:53248
	ds_read_b128 v[198:201], v210 offset:54272
	ds_read_b128 v[202:205], v210 offset:55296
	ds_read_b128 v[212:215], v210 offset:56320
	s_mov_b32 m0, s12
	s_nop 0
	global_load_lds_dwordx4 v162, s[4:5]
	s_add_i32 m0, s12, 0x2000
	s_nop 0
	global_load_lds_dwordx4 v206, s[4:5]
	s_add_u32 s4, s10, 0x80080
	s_addc_u32 s5, s11, 0
	s_add_i32 s10, s57, s17
	s_mov_b32 m0, s10
	s_nop 0
	global_load_lds_dwordx4 v162, s[4:5]
	s_add_i32 m0, s10, 0x2000
	s_nop 0
	global_load_lds_dwordx4 v206, s[4:5]
	s_mov_b32 m0, s26
	s_nop 0
	global_load_lds_dwordx4 v1, s[8:9]
	s_mov_b32 m0, s27
	s_nop 0
	global_load_lds_dwordx4 v164, s[8:9]
	s_waitcnt vmcnt(8)
	s_waitcnt lgkmcnt(0)
	s_barrier
	s_setprio 1
	s_waitcnt lgkmcnt(0)
	v_mfma_f32_16x16x32_bf16 v[110:113], v[74:77], v[178:181], v[110:113]
	v_mfma_f32_16x16x32_bf16 v[110:113], v[78:81], v[182:185], v[110:113]
	v_mfma_f32_16x16x32_bf16 v[106:109], v[98:101], v[178:181], v[106:109]
	v_mfma_f32_16x16x32_bf16 v[106:109], v[102:105], v[182:185], v[106:109]
	v_mfma_f32_16x16x32_bf16 v[94:97], v[74:77], v[186:189], v[94:97]
	v_mfma_f32_16x16x32_bf16 v[94:97], v[78:81], v[190:193], v[94:97]
	v_mfma_f32_16x16x32_bf16 v[90:93], v[98:101], v[186:189], v[90:93]
	v_mfma_f32_16x16x32_bf16 v[90:93], v[102:105], v[190:193], v[90:93]
	v_mfma_f32_16x16x32_bf16 v[22:25], v[146:149], v[186:189], v[22:25]
	v_mfma_f32_16x16x32_bf16 v[22:25], v[150:153], v[190:193], v[22:25]
	v_mfma_f32_16x16x32_bf16 v[18:21], v[154:157], v[186:189], v[18:21]
	v_mfma_f32_16x16x32_bf16 v[18:21], v[158:161], v[190:193], v[18:21]
	v_mfma_f32_16x16x32_bf16 v[86:89], v[74:77], v[194:197], v[86:89]
	v_mfma_f32_16x16x32_bf16 v[86:89], v[78:81], v[198:201], v[86:89]
	v_mfma_f32_16x16x32_bf16 v[82:85], v[98:101], v[194:197], v[82:85]
	v_mfma_f32_16x16x32_bf16 v[82:85], v[102:105], v[198:201], v[82:85]
	v_mfma_f32_16x16x32_bf16 v[14:17], v[146:149], v[194:197], v[14:17]
	v_mfma_f32_16x16x32_bf16 v[14:17], v[150:153], v[198:201], v[14:17]
	v_mfma_f32_16x16x32_bf16 v[10:13], v[154:157], v[194:197], v[10:13]
	v_mfma_f32_16x16x32_bf16 v[10:13], v[158:161], v[198:201], v[10:13]
	v_mfma_f32_16x16x32_bf16 v[26:29], v[74:77], v[202:205], v[26:29]
	v_mfma_f32_16x16x32_bf16 v[78:81], v[78:81], v[212:215], v[26:29]
	v_mfma_f32_16x16x32_bf16 v[26:29], v[98:101], v[202:205], v[30:33]
	v_mfma_f32_16x16x32_bf16 v[74:77], v[102:105], v[212:215], v[26:29]
	v_mfma_f32_16x16x32_bf16 v[6:9], v[146:149], v[202:205], v[6:9]
	v_mfma_f32_16x16x32_bf16 v[6:9], v[150:153], v[212:215], v[6:9]
	v_mfma_f32_16x16x32_bf16 v[2:5], v[154:157], v[202:205], v[2:5]
	v_mfma_f32_16x16x32_bf16 v[2:5], v[158:161], v[212:215], v[2:5]
	v_mfma_f32_16x16x32_bf16 v[26:29], v[146:149], v[178:181], v[38:41]
	v_mfma_f32_16x16x32_bf16 v[38:41], v[150:153], v[182:185], v[26:29]
	v_mfma_f32_16x16x32_bf16 v[26:29], v[154:157], v[178:181], v[34:37]
	v_mfma_f32_16x16x32_bf16 v[34:37], v[158:161], v[182:185], v[26:29]
	s_setprio 0
	s_barrier
;     __device__ __forceinline__ void operator()(const f32x4 (&acc)[2][2][4][2], const Unit& u, int wr, int wc, int fr, int fq) const {
;         const int row0 = u.pm * BM + wr * 64 + fr, col0 = u.pn * BM + wc * 32 + 8 * fq, b = (u.pm * BM) / rows_per_batch;
;         const float* g = gate + (size_t)b * gate_bstride + col0;
;         float ssq[2][4];
; #pragma unroll
;         for (int ai = 0; ai < 2; ++ai)
; #pragma unroll
;             for (int m = 0; m < 4; ++m) ssq[ai][m] = 0.f;
;         f32x4 gv[2][2], Gv[2][2];
; #pragma unroll
;         for (int bj = 0; bj < 2; ++bj) { gv[bj][0] = *(const f32x4*)(g + bj * HALF); gv[bj][1] = *(const f32x4*)(g + bj * HALF + 4); Gv[bj][0] = (f32x4){0.f, 0.f, 0.f, 0.f}; Gv[bj][1] = (f32x4){0.f, 0.f, 0.f, 0.f};
;             if (Hn) { const float* sc = scnext + (size_t)b * gate_bstride + col0 + bj * HALF;
;                 Gv[bj][0] = *(const f32x4*)(gnext + col0 + bj * HALF) * (1.0f + *(const f32x4*)(sc)); Gv[bj][1] = *(const f32x4*)(gnext + col0 + bj * HALF + 4) * (1.0f + *(const f32x4*)(sc + 4)); } }
; #pragma unroll
;         for (int bj = 0; bj < 2; ++bj) {
;             const f32x4 g0 = gv[bj][0], g1 = gv[bj][1], G0 = Gv[bj][0], G1 = Gv[bj][1];
; #pragma unroll
;             for (int ai = 0; ai < 2; ++ai)
; #pragma unroll
;                 for (int m = 0; m < 4; ++m) { const size_t off = (size_t)(row0 + ai * HALF + m * 16) * 2048 + col0 + bj * HALF;
;                     f32x4 x0 = __builtin_nontemporal_load((const f32x4*)(base + off)), x1 = __builtin_nontemporal_load((const f32x4*)(base + off + 4));
;                     if constexpr (HAS_DIN) { const u32x4 dw = __builtin_nontemporal_load((const u32x4*)(dbuf + off));
;                         x0 += (f32x4){__builtin_bit_cast(float, dw.x << 16), __builtin_bit_cast(float, dw.x & 0xffff0000u), __builtin_bit_cast(float, dw.y << 16), __builtin_bit_cast(float, dw.y & 0xffff0000u)};
;                         x1 += (f32x4){__builtin_bit_cast(float, dw.z << 16), __builtin_bit_cast(float, dw.z & 0xffff0000u), __builtin_bit_cast(float, dw.w << 16), __builtin_bit_cast(float, dw.w & 0xffff0000u)}; }
;                     f32x4 o0, o1;
;                     if constexpr (OUT_DELTA) { const f32x4 d0 = g0 * acc[ai][bj][m][0], d1 = g1 * acc[ai][bj][m][1];
	s_add_i32 s51, s51, 2
	s_add_u32 s40, s40, 0x100
	s_addc_u32 s49, s49, 0
	s_cmp_gt_u32 s51, 29
	s_mov_b64 s[4:5], s[6:7]
	s_cbranch_scc0 .LBB0_555
	s_ashr_i32 s4, s29, 31
	s_lshr_b32 s4, s4, 27
	s_add_i32 s4, s29, s4
	s_ashr_i32 s4, s4, 5
	v_lshl_or_b32 v148, s33, 8, v209
	s_mul_i32 s7, s4, 0xc000
	v_ashrrev_i32_e32 v149, 31, v148
	s_mul_hi_i32 s6, s4, 0xc000
	s_add_u32 s4, s22, s7
	s_addc_u32 s5, s23, s6
	v_lshlrev_b64 v[26:27], 2, v[148:149]
	v_lshl_add_u64 v[146:147], s[4:5], 0, v[26:27]
	s_add_u32 s4, s24, s7
	s_addc_u32 s5, s25, s6
	v_lshl_add_u64 v[160:161], s[4:5], 0, v[26:27]
	v_lshl_add_u64 v[178:179], s[46:47], 0, v[26:27]
	global_load_dwordx4 v[98:101], v[146:147], off offset:16
	global_load_dwordx4 v[102:105], v[146:147], off
	global_load_dwordx4 v[26:29], v[178:179], off offset:16
	global_load_dwordx4 v[30:33], v[178:179], off
	global_load_dwordx4 v[150:153], v[160:161], off offset:16
	global_load_dwordx4 v[154:157], v[160:161], off
	s_mov_b64 s[4:5], 0x40000
	s_waitcnt vmcnt(0)
	v_pk_mul_f32 v[188:189], v[140:141], v[100:101]
	v_pk_mul_f32 v[142:143], v[142:143], v[102:103]
	v_pk_mul_f32 v[144:145], v[144:145], v[104:105]
	v_pk_mul_f32 v[140:141], v[138:139], v[98:99]
	v_pk_mul_f32 v[136:137], v[136:137], v[104:105]
	v_pk_add_f32 v[156:157], v[156:157], 1.0 op_sel_hi:[1,0]
	v_pk_add_f32 v[154:155], v[154:155], 1.0 op_sel_hi:[1,0]
	v_pk_mul_f32 v[198:199], v[32:33], v[156:157]
	v_pk_mul_f32 v[200:201], v[30:31], v[154:155]
	v_pk_add_f32 v[30:31], v[152:153], 1.0 op_sel_hi:[1,0]
	v_pk_add_f32 v[32:33], v[150:151], 1.0 op_sel_hi:[1,0]
	v_pk_mul_f32 v[202:203], v[28:29], v[30:31]
	v_pk_mul_f32 v[204:205], v[26:27], v[32:33]
	global_load_dwordx4 v[26:29], v[146:147], off offset:528
	global_load_dwordx4 v[30:33], v[146:147], off offset:512
	global_load_dwordx4 v[156:159], v[178:179], off offset:528
	global_load_dwordx4 v[152:155], v[178:179], off offset:512
	s_nop 0
	global_load_dwordx4 v[178:181], v[160:161], off offset:528
	global_load_dwordx4 v[182:185], v[160:161], off offset:512
	v_pk_mul_f32 v[134:135], v[134:135], v[102:103]
	v_pk_mul_f32 v[130:131], v[130:131], v[98:99]
	v_pk_mul_f32 v[132:133], v[132:133], v[100:101]
	v_pk_mul_f32 v[128:129], v[128:129], v[104:105]
	v_pk_mul_f32 v[126:127], v[126:127], v[102:103]
	v_pk_mul_f32 v[122:123], v[122:123], v[98:99]
	v_pk_mul_f32 v[124:125], v[124:125], v[100:101]
	v_pk_mul_f32 v[120:121], v[120:121], v[104:105]
	v_pk_mul_f32 v[118:119], v[118:119], v[102:103]
	v_pk_mul_f32 v[114:115], v[114:115], v[98:99]
	v_pk_mul_f32 v[116:117], v[116:117], v[100:101]
	v_pk_mul_f32 v[112:113], v[112:113], v[104:105]
	v_pk_mul_f32 v[110:111], v[110:111], v[102:103]
	v_pk_mul_f32 v[106:107], v[106:107], v[98:99]
	v_pk_mul_f32 v[108:109], v[108:109], v[100:101]
	v_pk_mul_f32 v[96:97], v[96:97], v[104:105]
	v_pk_mul_f32 v[94:95], v[94:95], v[102:103]
	v_pk_mul_f32 v[90:91], v[90:91], v[98:99]
	v_pk_mul_f32 v[92:93], v[92:93], v[100:101]
	v_pk_mul_f32 v[88:89], v[88:89], v[104:105]
	v_pk_mul_f32 v[86:87], v[86:87], v[102:103]
	v_pk_mul_f32 v[82:83], v[82:83], v[98:99]
	v_pk_mul_f32 v[84:85], v[84:85], v[100:101]
	v_pk_mul_f32 v[80:81], v[80:81], v[104:105]
	v_pk_mul_f32 v[78:79], v[78:79], v[102:103]
	v_pk_mul_f32 v[74:75], v[74:75], v[98:99]
	v_pk_mul_f32 v[76:77], v[76:77], v[100:101]
	s_waitcnt vmcnt(5)
	v_pk_mul_f32 v[58:59], v[58:59], v[26:27]
	s_waitcnt vmcnt(4)
	v_pk_mul_f32 v[72:73], v[72:73], v[32:33]
	v_pk_mul_f32 v[70:71], v[70:71], v[30:31]
	v_pk_mul_f32 v[64:65], v[64:65], v[32:33]
	v_pk_mul_f32 v[62:63], v[62:63], v[30:31]
	s_waitcnt vmcnt(0)
	v_pk_add_f32 v[146:147], v[184:185], 1.0 op_sel_hi:[1,0]
	v_pk_add_f32 v[160:161], v[182:183], 1.0 op_sel_hi:[1,0]
	v_pk_mul_f32 v[150:151], v[154:155], v[146:147]
	v_pk_add_f32 v[146:147], v[180:181], 1.0 op_sel_hi:[1,0]
	v_pk_mul_f32 v[152:153], v[152:153], v[160:161]
	v_pk_mul_f32 v[154:155], v[158:159], v[146:147]
	v_lshl_add_u32 v146, s29, 8, v207
	v_ashrrev_i32_e32 v147, 31, v146
	v_lshlrev_b64 v[184:185], 11, v[146:147]
	v_lshl_add_u64 v[186:187], v[184:185], 0, v[148:149]
	v_pk_add_f32 v[160:161], v[178:179], 1.0 op_sel_hi:[1,0]
	v_lshl_add_u64 v[178:179], v[186:187], 2, s[44:45]
	v_pk_mul_f32 v[156:157], v[156:157], v[160:161]
	global_load_dwordx4 v[158:161], v[178:179], off nt
	global_load_dwordx4 v[180:183], v[178:179], off offset:16 nt
	v_cvt_pk_bf16_f32 v138, v142, v143
	v_lshlrev_b64 v[142:143], 1, v[186:187]
	v_cvt_pk_bf16_f32 v139, v144, v145
	v_cvt_pk_bf16_f32 v140, v140, v141
	v_cvt_pk_bf16_f32 v141, v188, v189
	v_lshl_add_u64 v[144:145], s[90:91], 0, v[142:143]
	global_store_dwordx4 v[144:145], v[138:141], off
	v_lshlrev_b32_e32 v144, 16, v140
	v_and_b32_e32 v145, 0xffff0000, v140
	v_lshlrev_b32_e32 v140, 16, v141
	v_and_b32_e32 v141, 0xffff0000, v141
	v_lshl_add_u64 v[142:143], s[96:97], 0, v[142:143]
	v_pk_mul_f32 v[60:61], v[60:61], v[28:29]
	v_pk_mul_f32 v[56:57], v[56:57], v[32:33]
	v_pk_mul_f32 v[54:55], v[54:55], v[30:31]
	v_pk_mul_f32 v[50:51], v[50:51], v[26:27]
	v_pk_mul_f32 v[52:53], v[52:53], v[28:29]
	v_pk_mul_f32 v[48:49], v[48:49], v[32:33]
	v_pk_mul_f32 v[46:47], v[46:47], v[30:31]
	v_pk_mul_f32 v[42:43], v[42:43], v[26:27]
	v_pk_mul_f32 v[44:45], v[44:45], v[28:29]
	v_pk_mul_f32 v[40:41], v[40:41], v[32:33]
	v_pk_mul_f32 v[38:39], v[38:39], v[30:31]
	v_pk_mul_f32 v[34:35], v[34:35], v[26:27]
	v_pk_mul_f32 v[36:37], v[36:37], v[28:29]
	v_pk_mul_f32 v[24:25], v[24:25], v[32:33]
	v_pk_mul_f32 v[22:23], v[22:23], v[30:31]
	v_pk_mul_f32 v[18:19], v[18:19], v[26:27]
	v_pk_mul_f32 v[20:21], v[20:21], v[28:29]
	v_pk_mul_f32 v[16:17], v[16:17], v[32:33]
	v_pk_mul_f32 v[14:15], v[14:15], v[30:31]
	v_pk_mul_f32 v[10:11], v[10:11], v[26:27]
	v_pk_mul_f32 v[12:13], v[12:13], v[28:29]
	v_pk_mul_f32 v[8:9], v[8:9], v[32:33]
	v_pk_mul_f32 v[6:7], v[6:7], v[30:31]
	v_pk_mul_f32 v[2:3], v[2:3], v[26:27]
	v_pk_mul_f32 v[4:5], v[4:5], v[28:29]
	s_waitcnt vmcnt(1)
; __device__ __forceinline__ unsigned cvt_pk_bf16(float lo, float hi) { unsigned r; asm volatile("v_cvt_pk_bf16_f32 %0, %1, %2" : "=v"(r) : "v"(lo), "v"(hi)); return r; }
;     __device__ __forceinline__ void operator()(const f32x4 (&acc)[2][2][4][2], const Unit& u, int wr, int wc, int fr, int fq) const {
;     ...
;                 for (int m = 0; m < 4; ++m) { const size_t off = (size_t)(row0 + ai * HALF + m * 16) * 2048 + col0 + bj * HALF;
;                     f32x4 x0 = __builtin_nontemporal_load((const f32x4*)(base + off)), x1 = __builtin_nontemporal_load((const f32x4*)(base + off + 4));
;                     if constexpr (HAS_DIN) { const u32x4 dw = __builtin_nontemporal_load((const u32x4*)(dbuf + off));
;                         x0 += (f32x4){__builtin_bit_cast(float, dw.x << 16), __builtin_bit_cast(float, dw.x & 0xffff0000u), __builtin_bit_cast(float, dw.y << 16), __builtin_bit_cast(float, dw.y & 0xffff0000u)};
;                         x1 += (f32x4){__builtin_bit_cast(float, dw.z << 16), __builtin_bit_cast(float, dw.z & 0xffff0000u), __builtin_bit_cast(float, dw.w << 16), __builtin_bit_cast(float, dw.w & 0xffff0000u)}; }
;                     f32x4 o0, o1;
;                     if constexpr (OUT_DELTA) { const f32x4 d0 = g0 * acc[ai][bj][m][0], d1 = g1 * acc[ai][bj][m][1];
;                         u32x4 w; w.x = cvt_pk_bf16(d0[0], d0[1]); w.y = cvt_pk_bf16(d0[2], d0[3]); w.z = cvt_pk_bf16(d1[0], d1[1]); w.w = cvt_pk_bf16(d1[2], d1[3]);
;                         *(u32x4*)(dbuf + off) = w;
;                         o0 = x0 + (f32x4){__builtin_bit_cast(float, w.x << 16), __builtin_bit_cast(float, w.x & 0xffff0000u), __builtin_bit_cast(float, w.y << 16), __builtin_bit_cast(float, w.y & 0xffff0000u)};
;                         o1 = x1 + (f32x4){__builtin_bit_cast(float, w.z << 16), __builtin_bit_cast(float, w.z & 0xffff0000u), __builtin_bit_cast(float, w.w << 16), __builtin_bit_cast(float, w.w & 0xffff0000u)}; }
;                     else { o0 = x0 + g0 * acc[ai][bj][m][0]; o1 = x1 + g1 * acc[ai][bj][m][1]; *(f32x4*)(out + off) = o0; *(f32x4*)(out + off + 4) = o1; }
;                     if (Hn) { const f32x4 h0 = o0 * G0, h1 = o1 * G1;
;                         u32x4 w; w.x = cvt_pk_bf16(h0[0], h0[1]); w.y = cvt_pk_bf16(h0[2], h0[3]); w.z = cvt_pk_bf16(h1[0], h1[1]); w.w = cvt_pk_bf16(h1[2], h1[3]);
;                         *(u32x4*)(Hn + off) = w;
	v_pk_add_f32 v[182:183], v[182:183], v[140:141]
	v_lshlrev_b32_e32 v140, 16, v138
	v_and_b32_e32 v141, 0xffff0000, v138
	v_lshlrev_b32_e32 v138, 16, v139
	v_and_b32_e32 v139, 0xffff0000, v139
	v_pk_add_f32 v[158:159], v[158:159], v[140:141]
	v_pk_add_f32 v[160:161], v[160:161], v[138:139]
	v_pk_mul_f32 v[138:139], v[200:201], v[158:159]
	v_pk_add_f32 v[144:145], v[180:181], v[144:145]
	v_pk_mul_f32 v[140:141], v[198:199], v[160:161]
	v_cvt_pk_bf16_f32 v138, v138, v139
	v_pk_mul_f32 v[180:181], v[202:203], v[182:183]
	v_cvt_pk_bf16_f32 v139, v140, v141
	v_pk_mul_f32 v[186:187], v[204:205], v[144:145]
	s_nop 0
	v_cvt_pk_bf16_f32 v140, v186, v187
	v_cvt_pk_bf16_f32 v141, v180, v181
	global_store_dwordx4 v[142:143], v[138:141], off
	s_nop 1
	v_mul_f32_e32 v138, v159, v159
	v_mul_f32_e32 v139, v161, v161
	v_fmac_f32_e32 v138, v158, v158
	v_fmac_f32_e32 v139, v160, v160
	v_add_f32_e32 v138, v138, v139
	v_mul_f32_e32 v139, v145, v145
	v_mul_f32_e32 v140, v183, v183
	v_fmac_f32_e32 v139, v144, v144
	v_fmac_f32_e32 v140, v182, v182
	v_add_f32_e32 v139, v139, v140
	v_add_f32_e32 v211, v138, v139
	v_or_b32_e32 v138, 16, v146
	v_ashrrev_i32_e32 v139, 31, v138
	v_lshlrev_b64 v[140:141], 11, v[138:139]
	v_lshl_add_u64 v[180:181], v[140:141], 0, v[148:149]
	v_lshl_add_u64 v[138:139], v[180:181], 2, s[44:45]
	global_load_dwordx4 v[142:145], v[138:139], off nt
	global_load_dwordx4 v[158:161], v[138:139], off offset:16 nt
	v_lshlrev_b64 v[180:181], 1, v[180:181]
	v_cvt_pk_bf16_f32 v134, v134, v135
	v_cvt_pk_bf16_f32 v135, v136, v137
	v_cvt_pk_bf16_f32 v136, v130, v131
	v_cvt_pk_bf16_f32 v137, v132, v133
	v_lshl_add_u64 v[130:131], s[90:91], 0, v[180:181]
	global_store_dwordx4 v[130:131], v[134:137], off
	v_lshlrev_b32_e32 v132, 16, v136
	v_and_b32_e32 v133, 0xffff0000, v136
	v_lshlrev_b32_e32 v130, 16, v137
	v_and_b32_e32 v131, 0xffff0000, v137
	v_lshlrev_b32_e32 v136, 16, v134
	v_and_b32_e32 v137, 0xffff0000, v134
	v_lshlrev_b32_e32 v134, 16, v135
	v_and_b32_e32 v135, 0xffff0000, v135
	s_waitcnt vmcnt(2)
	v_pk_add_f32 v[134:135], v[144:145], v[134:135]
	s_waitcnt vmcnt(1)
	v_pk_add_f32 v[130:131], v[160:161], v[130:131]
	v_pk_add_f32 v[136:137], v[142:143], v[136:137]
	v_pk_add_f32 v[132:133], v[158:159], v[132:133]
	v_pk_mul_f32 v[144:145], v[198:199], v[134:135]
	v_pk_mul_f32 v[142:143], v[200:201], v[136:137]
	v_pk_mul_f32 v[158:159], v[202:203], v[130:131]
	v_pk_mul_f32 v[160:161], v[204:205], v[132:133]
	v_cvt_pk_bf16_f32 v142, v142, v143
	v_cvt_pk_bf16_f32 v143, v144, v145
	s_nop 0
	v_cvt_pk_bf16_f32 v144, v160, v161
	v_cvt_pk_bf16_f32 v145, v158, v159
	v_lshl_add_u64 v[158:159], s[96:97], 0, v[180:181]
	global_store_dwordx4 v[158:159], v[142:145], off
	s_nop 1
	v_or_b32_e32 v142, 32, v146
	v_ashrrev_i32_e32 v143, 31, v142
	v_lshlrev_b64 v[144:145], 11, v[142:143]
	v_lshl_add_u64 v[186:187], v[144:145], 0, v[148:149]
	v_lshl_add_u64 v[142:143], v[186:187], 2, s[44:45]
	global_load_dwordx4 v[158:161], v[142:143], off nt
	global_load_dwordx4 v[180:183], v[142:143], off offset:16 nt
	v_lshlrev_b64 v[186:187], 1, v[186:187]
	v_cvt_pk_bf16_f32 v126, v126, v127
	v_cvt_pk_bf16_f32 v127, v128, v129
	v_cvt_pk_bf16_f32 v128, v122, v123
	v_cvt_pk_bf16_f32 v129, v124, v125
	v_lshl_add_u64 v[122:123], s[90:91], 0, v[186:187]
	global_store_dwordx4 v[122:123], v[126:129], off
	v_lshlrev_b32_e32 v124, 16, v128
	v_and_b32_e32 v125, 0xffff0000, v128
	v_lshlrev_b32_e32 v122, 16, v129
	v_and_b32_e32 v123, 0xffff0000, v129
	v_lshlrev_b32_e32 v128, 16, v126
	v_and_b32_e32 v129, 0xffff0000, v126
	v_lshlrev_b32_e32 v126, 16, v127
	v_and_b32_e32 v127, 0xffff0000, v127
	s_waitcnt vmcnt(2)
	v_pk_add_f32 v[126:127], v[160:161], v[126:127]
	s_waitcnt vmcnt(1)
	v_pk_add_f32 v[122:123], v[182:183], v[122:123]
	v_pk_add_f32 v[128:129], v[158:159], v[128:129]
	v_pk_add_f32 v[124:125], v[180:181], v[124:125]
	v_pk_mul_f32 v[160:161], v[198:199], v[126:127]
	v_pk_mul_f32 v[158:159], v[200:201], v[128:129]
	v_pk_mul_f32 v[180:181], v[202:203], v[122:123]
	v_pk_mul_f32 v[182:183], v[204:205], v[124:125]
	v_cvt_pk_bf16_f32 v158, v158, v159
	v_cvt_pk_bf16_f32 v159, v160, v161
	s_nop 0
	v_cvt_pk_bf16_f32 v160, v182, v183
	v_cvt_pk_bf16_f32 v161, v180, v181
	v_lshl_add_u64 v[180:181], s[96:97], 0, v[186:187]
	global_store_dwordx4 v[180:181], v[158:161], off
	s_nop 1
	v_or_b32_e32 v158, 48, v146
	v_ashrrev_i32_e32 v159, 31, v158
	v_lshlrev_b64 v[160:161], 11, v[158:159]
	v_lshl_add_u64 v[190:191], v[160:161], 0, v[148:149]
	v_lshl_add_u64 v[158:159], v[190:191], 2, s[44:45]
	global_load_dwordx4 v[180:183], v[158:159], off nt
	global_load_dwordx4 v[186:189], v[158:159], off offset:16 nt
	v_lshlrev_b64 v[190:191], 1, v[190:191]
	v_cvt_pk_bf16_f32 v118, v118, v119
	v_cvt_pk_bf16_f32 v119, v120, v121
	v_cvt_pk_bf16_f32 v120, v114, v115
	v_cvt_pk_bf16_f32 v121, v116, v117
	v_lshl_add_u64 v[114:115], s[90:91], 0, v[190:191]
	global_store_dwordx4 v[114:115], v[118:121], off
	v_lshlrev_b32_e32 v116, 16, v120
	v_and_b32_e32 v117, 0xffff0000, v120
	v_lshlrev_b32_e32 v114, 16, v121
	v_and_b32_e32 v115, 0xffff0000, v121
	v_lshlrev_b32_e32 v120, 16, v118
	v_and_b32_e32 v121, 0xffff0000, v118
	v_lshlrev_b32_e32 v118, 16, v119
	v_and_b32_e32 v119, 0xffff0000, v119
	s_waitcnt vmcnt(2)
	v_pk_add_f32 v[118:119], v[182:183], v[118:119]
	s_waitcnt vmcnt(1)
; __device__ __forceinline__ unsigned cvt_pk_bf16(float lo, float hi) { unsigned r; asm volatile("v_cvt_pk_bf16_f32 %0, %1, %2" : "=v"(r) : "v"(lo), "v"(hi)); return r; }
;     __device__ __forceinline__ void operator()(const f32x4 (&acc)[2][2][4][2], const Unit& u, int wr, int wc, int fr, int fq) const {
;     ...
;                 for (int m = 0; m < 4; ++m) { const size_t off = (size_t)(row0 + ai * HALF + m * 16) * 2048 + col0 + bj * HALF;
;                     f32x4 x0 = __builtin_nontemporal_load((const f32x4*)(base + off)), x1 = __builtin_nontemporal_load((const f32x4*)(base + off + 4));
;                     if constexpr (HAS_DIN) { const u32x4 dw = __builtin_nontemporal_load((const u32x4*)(dbuf + off));
;                         x0 += (f32x4){__builtin_bit_cast(float, dw.x << 16), __builtin_bit_cast(float, dw.x & 0xffff0000u), __builtin_bit_cast(float, dw.y << 16), __builtin_bit_cast(float, dw.y & 0xffff0000u)};
;                         x1 += (f32x4){__builtin_bit_cast(float, dw.z << 16), __builtin_bit_cast(float, dw.z & 0xffff0000u), __builtin_bit_cast(float, dw.w << 16), __builtin_bit_cast(float, dw.w & 0xffff0000u)}; }
;                     f32x4 o0, o1;
;                     if constexpr (OUT_DELTA) { const f32x4 d0 = g0 * acc[ai][bj][m][0], d1 = g1 * acc[ai][bj][m][1];
;                         u32x4 w; w.x = cvt_pk_bf16(d0[0], d0[1]); w.y = cvt_pk_bf16(d0[2], d0[3]); w.z = cvt_pk_bf16(d1[0], d1[1]); w.w = cvt_pk_bf16(d1[2], d1[3]);
;                         *(u32x4*)(dbuf + off) = w;
;                         o0 = x0 + (f32x4){__builtin_bit_cast(float, w.x << 16), __builtin_bit_cast(float, w.x & 0xffff0000u), __builtin_bit_cast(float, w.y << 16), __builtin_bit_cast(float, w.y & 0xffff0000u)};
;                         o1 = x1 + (f32x4){__builtin_bit_cast(float, w.z << 16), __builtin_bit_cast(float, w.z & 0xffff0000u), __builtin_bit_cast(float, w.w << 16), __builtin_bit_cast(float, w.w & 0xffff0000u)}; }
;                     else { o0 = x0 + g0 * acc[ai][bj][m][0]; o1 = x1 + g1 * acc[ai][bj][m][1]; *(f32x4*)(out + off) = o0; *(f32x4*)(out + off + 4) = o1; }
;                     if (Hn) { const f32x4 h0 = o0 * G0, h1 = o1 * G1;
;                         u32x4 w; w.x = cvt_pk_bf16(h0[0], h0[1]); w.y = cvt_pk_bf16(h0[2], h0[3]); w.z = cvt_pk_bf16(h1[0], h1[1]); w.w = cvt_pk_bf16(h1[2], h1[3]);
;                         *(u32x4*)(Hn + off) = w;
	v_pk_add_f32 v[114:115], v[188:189], v[114:115]
	v_pk_add_f32 v[120:121], v[180:181], v[120:121]
	v_pk_add_f32 v[116:117], v[186:187], v[116:117]
	v_pk_mul_f32 v[182:183], v[198:199], v[118:119]
	v_pk_mul_f32 v[180:181], v[200:201], v[120:121]
	v_pk_mul_f32 v[186:187], v[202:203], v[114:115]
	v_pk_mul_f32 v[188:189], v[204:205], v[116:117]
	v_cvt_pk_bf16_f32 v180, v180, v181
	v_cvt_pk_bf16_f32 v181, v182, v183
	s_nop 0
	v_cvt_pk_bf16_f32 v182, v188, v189
	v_cvt_pk_bf16_f32 v183, v186, v187
	v_lshl_add_u64 v[186:187], s[96:97], 0, v[190:191]
	global_store_dwordx4 v[186:187], v[180:183], off
	s_nop 1
	v_lshl_add_u64 v[182:183], v[184:185], 0, s[4:5]
	v_lshl_add_u64 v[194:195], v[182:183], 0, v[148:149]
	v_lshl_add_u64 v[180:181], v[194:195], 2, s[44:45]
	global_load_dwordx4 v[186:189], v[180:181], off nt
	global_load_dwordx4 v[190:193], v[180:181], off offset:16 nt
	v_lshlrev_b64 v[194:195], 1, v[194:195]
	v_cvt_pk_bf16_f32 v110, v110, v111
	v_cvt_pk_bf16_f32 v111, v112, v113
	v_cvt_pk_bf16_f32 v112, v106, v107
	v_cvt_pk_bf16_f32 v113, v108, v109
	v_lshl_add_u64 v[106:107], s[90:91], 0, v[194:195]
	global_store_dwordx4 v[106:107], v[110:113], off
	v_lshlrev_b32_e32 v108, 16, v112
	v_and_b32_e32 v109, 0xffff0000, v112
	v_lshlrev_b32_e32 v106, 16, v113
	v_and_b32_e32 v107, 0xffff0000, v113
	v_lshlrev_b32_e32 v112, 16, v110
	v_and_b32_e32 v113, 0xffff0000, v110
	v_lshlrev_b32_e32 v110, 16, v111
	v_and_b32_e32 v111, 0xffff0000, v111
	s_mov_b64 s[4:5], 0x48000
	s_waitcnt vmcnt(2)
	v_pk_add_f32 v[110:111], v[188:189], v[110:111]
	s_waitcnt vmcnt(1)
	v_pk_add_f32 v[106:107], v[192:193], v[106:107]
	v_pk_add_f32 v[112:113], v[186:187], v[112:113]
	v_pk_add_f32 v[108:109], v[190:191], v[108:109]
	v_pk_mul_f32 v[188:189], v[198:199], v[110:111]
	v_pk_mul_f32 v[186:187], v[200:201], v[112:113]
	v_pk_mul_f32 v[190:191], v[202:203], v[106:107]
	v_pk_mul_f32 v[192:193], v[204:205], v[108:109]
	v_cvt_pk_bf16_f32 v186, v186, v187
	v_cvt_pk_bf16_f32 v187, v188, v189
	s_nop 0
	v_cvt_pk_bf16_f32 v188, v192, v193
	v_cvt_pk_bf16_f32 v189, v190, v191
	v_lshl_add_u64 v[190:191], s[96:97], 0, v[194:195]
	global_store_dwordx4 v[190:191], v[186:189], off
	s_nop 1
	v_lshl_add_u64 v[188:189], v[184:185], 0, s[4:5]
	v_lshl_add_u64 v[212:213], v[188:189], 0, v[148:149]
	v_lshl_add_u64 v[186:187], v[212:213], 2, s[44:45]
	global_load_dwordx4 v[190:193], v[186:187], off nt
	global_load_dwordx4 v[194:197], v[186:187], off offset:16 nt
	v_lshlrev_b64 v[212:213], 1, v[212:213]
	v_cvt_pk_bf16_f32 v94, v94, v95
	v_cvt_pk_bf16_f32 v95, v96, v97
	v_cvt_pk_bf16_f32 v96, v90, v91
	v_cvt_pk_bf16_f32 v97, v92, v93
	v_lshl_add_u64 v[90:91], s[90:91], 0, v[212:213]
	global_store_dwordx4 v[90:91], v[94:97], off
	v_lshlrev_b32_e32 v92, 16, v96
	v_and_b32_e32 v93, 0xffff0000, v96
	v_lshlrev_b32_e32 v90, 16, v97
	v_and_b32_e32 v91, 0xffff0000, v97
	v_lshlrev_b32_e32 v96, 16, v94
	v_and_b32_e32 v97, 0xffff0000, v94
	v_lshlrev_b32_e32 v94, 16, v95
	v_and_b32_e32 v95, 0xffff0000, v95
	s_mov_b64 s[4:5], 0x50000
	s_waitcnt vmcnt(2)
	v_pk_add_f32 v[94:95], v[192:193], v[94:95]
	s_waitcnt vmcnt(1)
	v_pk_add_f32 v[90:91], v[196:197], v[90:91]
	v_pk_add_f32 v[96:97], v[190:191], v[96:97]
	v_pk_add_f32 v[92:93], v[194:195], v[92:93]
	v_pk_mul_f32 v[192:193], v[198:199], v[94:95]
	v_pk_mul_f32 v[190:191], v[200:201], v[96:97]
	v_pk_mul_f32 v[194:195], v[202:203], v[90:91]
	v_pk_mul_f32 v[196:197], v[204:205], v[92:93]
	v_cvt_pk_bf16_f32 v190, v190, v191
	v_cvt_pk_bf16_f32 v191, v192, v193
	s_nop 0
	v_cvt_pk_bf16_f32 v192, v196, v197
	v_cvt_pk_bf16_f32 v193, v194, v195
	v_lshl_add_u64 v[194:195], s[96:97], 0, v[212:213]
	global_store_dwordx4 v[194:195], v[190:193], off
	s_nop 1
	v_lshl_add_u64 v[192:193], v[184:185], 0, s[4:5]
	v_lshl_add_u64 v[220:221], v[192:193], 0, v[148:149]
	v_lshl_add_u64 v[190:191], v[220:221], 2, s[44:45]
	global_load_dwordx4 v[194:197], v[190:191], off nt
	global_load_dwordx4 v[212:215], v[190:191], off offset:16 nt
	v_lshlrev_b64 v[220:221], 1, v[220:221]
	v_cvt_pk_bf16_f32 v86, v86, v87
	v_cvt_pk_bf16_f32 v87, v88, v89
	v_cvt_pk_bf16_f32 v88, v82, v83
	v_cvt_pk_bf16_f32 v89, v84, v85
	v_lshl_add_u64 v[82:83], s[90:91], 0, v[220:221]
	global_store_dwordx4 v[82:83], v[86:89], off
	v_lshlrev_b32_e32 v84, 16, v88
	v_and_b32_e32 v85, 0xffff0000, v88
	v_lshlrev_b32_e32 v82, 16, v89
	v_and_b32_e32 v83, 0xffff0000, v89
	v_lshlrev_b32_e32 v88, 16, v86
	v_and_b32_e32 v89, 0xffff0000, v86
	v_lshlrev_b32_e32 v86, 16, v87
	v_and_b32_e32 v87, 0xffff0000, v87
	s_mov_b64 s[4:5], 0x58000
	s_waitcnt vmcnt(2)
	v_pk_add_f32 v[86:87], v[196:197], v[86:87]
	s_waitcnt vmcnt(1)
	v_pk_add_f32 v[82:83], v[214:215], v[82:83]
	v_pk_add_f32 v[88:89], v[194:195], v[88:89]
	v_pk_add_f32 v[84:85], v[212:213], v[84:85]
	v_pk_mul_f32 v[196:197], v[198:199], v[86:87]
	v_pk_mul_f32 v[194:195], v[200:201], v[88:89]
	v_pk_mul_f32 v[212:213], v[202:203], v[82:83]
	v_pk_mul_f32 v[214:215], v[204:205], v[84:85]
	v_cvt_pk_bf16_f32 v194, v194, v195
	v_cvt_pk_bf16_f32 v195, v196, v197
	s_nop 0
	v_cvt_pk_bf16_f32 v196, v214, v215
	v_cvt_pk_bf16_f32 v197, v212, v213
	v_lshl_add_u64 v[212:213], s[96:97], 0, v[220:221]
	global_store_dwordx4 v[212:213], v[194:197], off
	s_nop 1
	v_lshl_add_u64 v[196:197], v[184:185], 0, s[4:5]
	v_lshl_add_u64 v[224:225], v[196:197], 0, v[148:149]
	v_lshl_add_u64 v[194:195], v[224:225], 2, s[44:45]
	global_load_dwordx4 v[212:215], v[194:195], off nt
	global_load_dwordx4 v[220:223], v[194:195], off offset:16 nt
	v_lshlrev_b64 v[102:103], 1, v[224:225]
	v_cvt_pk_bf16_f32 v78, v78, v79
	v_cvt_pk_bf16_f32 v79, v80, v81
	v_cvt_pk_bf16_f32 v80, v74, v75
	v_cvt_pk_bf16_f32 v81, v76, v77
	v_lshl_add_u64 v[74:75], s[90:91], 0, v[102:103]
	global_store_dwordx4 v[74:75], v[78:81], off
	v_lshlrev_b32_e32 v76, 16, v80
	v_and_b32_e32 v77, 0xffff0000, v80
	v_lshlrev_b32_e32 v74, 16, v81
	v_and_b32_e32 v75, 0xffff0000, v81
	v_lshlrev_b32_e32 v80, 16, v78
	v_and_b32_e32 v81, 0xffff0000, v78
	v_lshlrev_b32_e32 v78, 16, v79
	v_and_b32_e32 v79, 0xffff0000, v79
	v_lshl_add_u64 v[102:103], s[96:97], 0, v[102:103]
	v_or_b32_e32 v148, 0x80, v148
	s_waitcnt vmcnt(2)
; __device__ __forceinline__ unsigned cvt_pk_bf16(float lo, float hi) { unsigned r; asm volatile("v_cvt_pk_bf16_f32 %0, %1, %2" : "=v"(r) : "v"(lo), "v"(hi)); return r; }
;     __device__ __forceinline__ void operator()(const f32x4 (&acc)[2][2][4][2], const Unit& u, int wr, int wc, int fr, int fq) const {
;     ...
;                 for (int m = 0; m < 4; ++m) { const size_t off = (size_t)(row0 + ai * HALF + m * 16) * 2048 + col0 + bj * HALF;
;                     f32x4 x0 = __builtin_nontemporal_load((const f32x4*)(base + off)), x1 = __builtin_nontemporal_load((const f32x4*)(base + off + 4));
;                     if constexpr (HAS_DIN) { const u32x4 dw = __builtin_nontemporal_load((const u32x4*)(dbuf + off));
;                         x0 += (f32x4){__builtin_bit_cast(float, dw.x << 16), __builtin_bit_cast(float, dw.x & 0xffff0000u), __builtin_bit_cast(float, dw.y << 16), __builtin_bit_cast(float, dw.y & 0xffff0000u)};
;                         x1 += (f32x4){__builtin_bit_cast(float, dw.z << 16), __builtin_bit_cast(float, dw.z & 0xffff0000u), __builtin_bit_cast(float, dw.w << 16), __builtin_bit_cast(float, dw.w & 0xffff0000u)}; }
;                     f32x4 o0, o1;
;                     if constexpr (OUT_DELTA) { const f32x4 d0 = g0 * acc[ai][bj][m][0], d1 = g1 * acc[ai][bj][m][1];
;                         u32x4 w; w.x = cvt_pk_bf16(d0[0], d0[1]); w.y = cvt_pk_bf16(d0[2], d0[3]); w.z = cvt_pk_bf16(d1[0], d1[1]); w.w = cvt_pk_bf16(d1[2], d1[3]);
;                         *(u32x4*)(dbuf + off) = w;
;                         o0 = x0 + (f32x4){__builtin_bit_cast(float, w.x << 16), __builtin_bit_cast(float, w.x & 0xffff0000u), __builtin_bit_cast(float, w.y << 16), __builtin_bit_cast(float, w.y & 0xffff0000u)};
;                         o1 = x1 + (f32x4){__builtin_bit_cast(float, w.z << 16), __builtin_bit_cast(float, w.z & 0xffff0000u), __builtin_bit_cast(float, w.w << 16), __builtin_bit_cast(float, w.w & 0xffff0000u)}; }
;                     else { o0 = x0 + g0 * acc[ai][bj][m][0]; o1 = x1 + g1 * acc[ai][bj][m][1]; *(f32x4*)(out + off) = o0; *(f32x4*)(out + off + 4) = o1; }
;                     if (Hn) { const f32x4 h0 = o0 * G0, h1 = o1 * G1;
;                         u32x4 w; w.x = cvt_pk_bf16(h0[0], h0[1]); w.y = cvt_pk_bf16(h0[2], h0[3]); w.z = cvt_pk_bf16(h1[0], h1[1]); w.w = cvt_pk_bf16(h1[2], h1[3]);
;                         *(u32x4*)(Hn + off) = w;
	v_pk_add_f32 v[78:79], v[214:215], v[78:79]
	v_pk_add_f32 v[80:81], v[212:213], v[80:81]
	s_waitcnt vmcnt(1)
	v_pk_add_f32 v[74:75], v[222:223], v[74:75]
	v_pk_add_f32 v[76:77], v[220:221], v[76:77]
	v_pk_mul_f32 v[100:101], v[198:199], v[78:79]
	v_pk_mul_f32 v[98:99], v[200:201], v[80:81]
	v_pk_mul_f32 v[104:105], v[202:203], v[74:75]
	v_pk_mul_f32 v[198:199], v[204:205], v[76:77]
	v_cvt_pk_bf16_f32 v98, v98, v99
	v_cvt_pk_bf16_f32 v99, v100, v101
	s_nop 0
	v_cvt_pk_bf16_f32 v100, v198, v199
	v_cvt_pk_bf16_f32 v101, v104, v105
	global_store_dwordx4 v[102:103], v[98:101], off
	global_load_dwordx4 v[100:103], v[178:179], off offset:512 nt
	global_load_dwordx4 v[198:201], v[178:179], off offset:528 nt
	v_lshl_add_u64 v[98:99], v[184:185], 0, v[148:149]
	v_pk_mul_f32 v[104:105], v[68:69], v[28:29]
	v_pk_mul_f32 v[68:69], v[66:67], v[26:27]
	v_cvt_pk_bf16_f32 v66, v70, v71
	v_cvt_pk_bf16_f32 v67, v72, v73
	s_nop 0
	v_cvt_pk_bf16_f32 v68, v68, v69
	v_cvt_pk_bf16_f32 v69, v104, v105
	v_lshlrev_b64 v[104:105], 1, v[98:99]
	v_lshl_add_u64 v[70:71], s[90:91], 0, v[104:105]
	global_store_dwordx4 v[70:71], v[66:69], off
	v_lshlrev_b32_e32 v72, 16, v68
	v_and_b32_e32 v73, 0xffff0000, v68
	v_lshlrev_b32_e32 v68, 16, v69
	v_and_b32_e32 v69, 0xffff0000, v69
	s_waitcnt vmcnt(1)
	v_pk_add_f32 v[70:71], v[200:201], v[68:69]
	v_lshlrev_b32_e32 v68, 16, v66
	v_and_b32_e32 v69, 0xffff0000, v66
	v_lshlrev_b32_e32 v66, 16, v67
	v_and_b32_e32 v67, 0xffff0000, v67
	v_pk_add_f32 v[98:99], v[102:103], v[66:67]
	v_pk_add_f32 v[100:101], v[100:101], v[68:69]
	v_pk_add_f32 v[72:73], v[198:199], v[72:73]
	v_pk_mul_f32 v[68:69], v[150:151], v[98:99]
	v_pk_mul_f32 v[66:67], v[152:153], v[100:101]
	v_pk_mul_f32 v[102:103], v[154:155], v[70:71]
	v_pk_mul_f32 v[178:179], v[156:157], v[72:73]
	v_cvt_pk_bf16_f32 v66, v66, v67
	v_cvt_pk_bf16_f32 v67, v68, v69
	s_nop 0
	v_cvt_pk_bf16_f32 v68, v178, v179
	v_cvt_pk_bf16_f32 v69, v102, v103
	v_lshl_add_u64 v[102:103], s[96:97], 0, v[104:105]
	global_store_dwordx4 v[102:103], v[66:69], off
	s_nop 1
	v_mul_f32_e32 v66, v101, v101
	v_mul_f32_e32 v67, v99, v99
	v_fmac_f32_e32 v66, v100, v100
	v_fmac_f32_e32 v67, v98, v98
	v_add_f32_e32 v66, v66, v67
	v_mul_f32_e32 v67, v73, v73
	v_mul_f32_e32 v68, v71, v71
	v_fmac_f32_e32 v67, v72, v72
	v_fmac_f32_e32 v68, v70, v70
	v_add_f32_e32 v67, v67, v68
	global_load_dwordx4 v[68:71], v[138:139], off offset:512 nt
	global_load_dwordx4 v[98:101], v[138:139], off offset:528 nt
	v_lshl_add_u64 v[72:73], v[140:141], 0, v[148:149]
	v_lshlrev_b64 v[72:73], 1, v[72:73]
	v_cvt_pk_bf16_f32 v62, v62, v63
	v_cvt_pk_bf16_f32 v63, v64, v65
	v_cvt_pk_bf16_f32 v64, v58, v59
	v_cvt_pk_bf16_f32 v65, v60, v61
	v_lshl_add_u64 v[58:59], s[90:91], 0, v[72:73]
	global_store_dwordx4 v[58:59], v[62:65], off
	v_lshlrev_b32_e32 v60, 16, v64
	v_and_b32_e32 v61, 0xffff0000, v64
	v_lshlrev_b32_e32 v58, 16, v65
	v_and_b32_e32 v59, 0xffff0000, v65
	v_lshlrev_b32_e32 v64, 16, v62
	v_and_b32_e32 v65, 0xffff0000, v62
	v_lshlrev_b32_e32 v62, 16, v63
	v_and_b32_e32 v63, 0xffff0000, v63
	v_lshl_add_u64 v[72:73], s[96:97], 0, v[72:73]
	v_add_f32_e32 v66, v66, v67
	v_add_f32_e32 v66, v211, v66
	s_waitcnt vmcnt(2)
	v_pk_add_f32 v[62:63], v[70:71], v[62:63]
	v_pk_add_f32 v[64:65], v[68:69], v[64:65]
	s_waitcnt vmcnt(1)
	v_pk_add_f32 v[58:59], v[100:101], v[58:59]
	v_pk_add_f32 v[60:61], v[98:99], v[60:61]
	v_pk_mul_f32 v[70:71], v[150:151], v[62:63]
	v_pk_mul_f32 v[68:69], v[152:153], v[64:65]
	v_pk_mul_f32 v[98:99], v[154:155], v[58:59]
	v_pk_mul_f32 v[100:101], v[156:157], v[60:61]
	v_cvt_pk_bf16_f32 v68, v68, v69
	v_cvt_pk_bf16_f32 v69, v70, v71
	s_nop 0
	v_cvt_pk_bf16_f32 v70, v100, v101
	v_cvt_pk_bf16_f32 v71, v98, v99
	global_store_dwordx4 v[72:73], v[68:71], off
	global_load_dwordx4 v[68:71], v[142:143], off offset:512 nt
	s_nop 0
	global_load_dwordx4 v[98:101], v[142:143], off offset:528 nt
	v_lshl_add_u64 v[72:73], v[144:145], 0, v[148:149]
	v_lshlrev_b64 v[72:73], 1, v[72:73]
	v_cvt_pk_bf16_f32 v54, v54, v55
	v_cvt_pk_bf16_f32 v55, v56, v57
	v_cvt_pk_bf16_f32 v56, v50, v51
	v_cvt_pk_bf16_f32 v57, v52, v53
	v_lshl_add_u64 v[50:51], s[90:91], 0, v[72:73]
	global_store_dwordx4 v[50:51], v[54:57], off
	v_lshlrev_b32_e32 v52, 16, v56
	v_and_b32_e32 v53, 0xffff0000, v56
	v_lshlrev_b32_e32 v50, 16, v57
	v_and_b32_e32 v51, 0xffff0000, v57
	v_lshlrev_b32_e32 v56, 16, v54
	v_and_b32_e32 v57, 0xffff0000, v54
	v_lshlrev_b32_e32 v54, 16, v55
	v_and_b32_e32 v55, 0xffff0000, v55
	v_lshl_add_u64 v[72:73], s[96:97], 0, v[72:73]
	s_waitcnt vmcnt(2)
	v_pk_add_f32 v[54:55], v[70:71], v[54:55]
	v_pk_add_f32 v[56:57], v[68:69], v[56:57]
	s_waitcnt vmcnt(1)
	v_pk_add_f32 v[50:51], v[100:101], v[50:51]
	v_pk_add_f32 v[52:53], v[98:99], v[52:53]
	v_pk_mul_f32 v[70:71], v[150:151], v[54:55]
	v_pk_mul_f32 v[68:69], v[152:153], v[56:57]
	v_pk_mul_f32 v[98:99], v[154:155], v[50:51]
	v_pk_mul_f32 v[100:101], v[156:157], v[52:53]
	v_cvt_pk_bf16_f32 v68, v68, v69
	v_cvt_pk_bf16_f32 v69, v70, v71
	s_nop 0
	v_cvt_pk_bf16_f32 v70, v100, v101
	v_cvt_pk_bf16_f32 v71, v98, v99
	global_store_dwordx4 v[72:73], v[68:71], off
	global_load_dwordx4 v[68:71], v[158:159], off offset:512 nt
	s_nop 0
	global_load_dwordx4 v[98:101], v[158:159], off offset:528 nt
	v_lshl_add_u64 v[72:73], v[160:161], 0, v[148:149]
	v_lshlrev_b64 v[72:73], 1, v[72:73]
	v_cvt_pk_bf16_f32 v46, v46, v47
	v_cvt_pk_bf16_f32 v47, v48, v49
	v_cvt_pk_bf16_f32 v48, v42, v43
	v_cvt_pk_bf16_f32 v49, v44, v45
	v_lshl_add_u64 v[42:43], s[90:91], 0, v[72:73]
	global_store_dwordx4 v[42:43], v[46:49], off
	v_lshlrev_b32_e32 v44, 16, v48
	v_and_b32_e32 v45, 0xffff0000, v48
	v_lshlrev_b32_e32 v42, 16, v49
	v_and_b32_e32 v43, 0xffff0000, v49
	v_lshlrev_b32_e32 v48, 16, v46
	v_and_b32_e32 v49, 0xffff0000, v46
	v_lshlrev_b32_e32 v46, 16, v47
	v_and_b32_e32 v47, 0xffff0000, v47
	v_lshl_add_u64 v[72:73], s[96:97], 0, v[72:73]
	s_waitcnt vmcnt(2)
; __device__ __forceinline__ unsigned cvt_pk_bf16(float lo, float hi) { unsigned r; asm volatile("v_cvt_pk_bf16_f32 %0, %1, %2" : "=v"(r) : "v"(lo), "v"(hi)); return r; }
;     __device__ __forceinline__ void operator()(const f32x4 (&acc)[2][2][4][2], const Unit& u, int wr, int wc, int fr, int fq) const {
;     ...
;                 for (int m = 0; m < 4; ++m) { const size_t off = (size_t)(row0 + ai * HALF + m * 16) * 2048 + col0 + bj * HALF;
;                     f32x4 x0 = __builtin_nontemporal_load((const f32x4*)(base + off)), x1 = __builtin_nontemporal_load((const f32x4*)(base + off + 4));
;                     if constexpr (HAS_DIN) { const u32x4 dw = __builtin_nontemporal_load((const u32x4*)(dbuf + off));
;                         x0 += (f32x4){__builtin_bit_cast(float, dw.x << 16), __builtin_bit_cast(float, dw.x & 0xffff0000u), __builtin_bit_cast(float, dw.y << 16), __builtin_bit_cast(float, dw.y & 0xffff0000u)};
;                         x1 += (f32x4){__builtin_bit_cast(float, dw.z << 16), __builtin_bit_cast(float, dw.z & 0xffff0000u), __builtin_bit_cast(float, dw.w << 16), __builtin_bit_cast(float, dw.w & 0xffff0000u)}; }
;                     f32x4 o0, o1;
;                     if constexpr (OUT_DELTA) { const f32x4 d0 = g0 * acc[ai][bj][m][0], d1 = g1 * acc[ai][bj][m][1];
;                         u32x4 w; w.x = cvt_pk_bf16(d0[0], d0[1]); w.y = cvt_pk_bf16(d0[2], d0[3]); w.z = cvt_pk_bf16(d1[0], d1[1]); w.w = cvt_pk_bf16(d1[2], d1[3]);
;                         *(u32x4*)(dbuf + off) = w;
;                         o0 = x0 + (f32x4){__builtin_bit_cast(float, w.x << 16), __builtin_bit_cast(float, w.x & 0xffff0000u), __builtin_bit_cast(float, w.y << 16), __builtin_bit_cast(float, w.y & 0xffff0000u)};
;                         o1 = x1 + (f32x4){__builtin_bit_cast(float, w.z << 16), __builtin_bit_cast(float, w.z & 0xffff0000u), __builtin_bit_cast(float, w.w << 16), __builtin_bit_cast(float, w.w & 0xffff0000u)}; }
;                     else { o0 = x0 + g0 * acc[ai][bj][m][0]; o1 = x1 + g1 * acc[ai][bj][m][1]; *(f32x4*)(out + off) = o0; *(f32x4*)(out + off + 4) = o1; }
;                     if (Hn) { const f32x4 h0 = o0 * G0, h1 = o1 * G1;
;                         u32x4 w; w.x = cvt_pk_bf16(h0[0], h0[1]); w.y = cvt_pk_bf16(h0[2], h0[3]); w.z = cvt_pk_bf16(h1[0], h1[1]); w.w = cvt_pk_bf16(h1[2], h1[3]);
;                         *(u32x4*)(Hn + off) = w;
	v_pk_add_f32 v[46:47], v[70:71], v[46:47]
	v_pk_add_f32 v[48:49], v[68:69], v[48:49]
	s_waitcnt vmcnt(1)
	v_pk_add_f32 v[42:43], v[100:101], v[42:43]
	v_pk_add_f32 v[44:45], v[98:99], v[44:45]
	v_pk_mul_f32 v[70:71], v[150:151], v[46:47]
	v_pk_mul_f32 v[68:69], v[152:153], v[48:49]
	v_pk_mul_f32 v[98:99], v[154:155], v[42:43]
	v_pk_mul_f32 v[100:101], v[156:157], v[44:45]
	v_cvt_pk_bf16_f32 v68, v68, v69
	v_cvt_pk_bf16_f32 v69, v70, v71
	s_nop 0
	v_cvt_pk_bf16_f32 v70, v100, v101
	v_cvt_pk_bf16_f32 v71, v98, v99
	global_store_dwordx4 v[72:73], v[68:71], off
	global_load_dwordx4 v[68:71], v[180:181], off offset:512 nt
	s_nop 0
	global_load_dwordx4 v[98:101], v[180:181], off offset:528 nt
	v_lshl_add_u64 v[72:73], v[182:183], 0, v[148:149]
	v_lshlrev_b64 v[72:73], 1, v[72:73]
	v_cvt_pk_bf16_f32 v38, v38, v39
	v_cvt_pk_bf16_f32 v39, v40, v41
	v_cvt_pk_bf16_f32 v40, v34, v35
	v_cvt_pk_bf16_f32 v41, v36, v37
	v_lshl_add_u64 v[34:35], s[90:91], 0, v[72:73]
	global_store_dwordx4 v[34:35], v[38:41], off
	v_lshlrev_b32_e32 v36, 16, v40
	v_and_b32_e32 v37, 0xffff0000, v40
	v_lshlrev_b32_e32 v34, 16, v41
	v_and_b32_e32 v35, 0xffff0000, v41
	v_lshlrev_b32_e32 v40, 16, v38
	v_and_b32_e32 v41, 0xffff0000, v38
	v_lshlrev_b32_e32 v38, 16, v39
	v_and_b32_e32 v39, 0xffff0000, v39
	v_lshl_add_u64 v[72:73], s[96:97], 0, v[72:73]
	s_waitcnt vmcnt(2)
	v_pk_add_f32 v[38:39], v[70:71], v[38:39]
	v_pk_add_f32 v[40:41], v[68:69], v[40:41]
	s_waitcnt vmcnt(1)
	v_pk_add_f32 v[34:35], v[100:101], v[34:35]
	v_pk_add_f32 v[36:37], v[98:99], v[36:37]
	v_pk_mul_f32 v[70:71], v[150:151], v[38:39]
	v_pk_mul_f32 v[68:69], v[152:153], v[40:41]
	v_pk_mul_f32 v[98:99], v[154:155], v[34:35]
	v_pk_mul_f32 v[100:101], v[156:157], v[36:37]
	v_cvt_pk_bf16_f32 v68, v68, v69
	v_cvt_pk_bf16_f32 v69, v70, v71
	s_nop 0
	v_cvt_pk_bf16_f32 v70, v100, v101
	v_cvt_pk_bf16_f32 v71, v98, v99
	global_store_dwordx4 v[72:73], v[68:71], off
	global_load_dwordx4 v[68:71], v[186:187], off offset:512 nt
	s_nop 0
	global_load_dwordx4 v[98:101], v[186:187], off offset:528 nt
	v_lshl_add_u64 v[72:73], v[188:189], 0, v[148:149]
	v_lshlrev_b64 v[72:73], 1, v[72:73]
	v_cvt_pk_bf16_f32 v22, v22, v23
	v_cvt_pk_bf16_f32 v23, v24, v25
	v_cvt_pk_bf16_f32 v24, v18, v19
	v_cvt_pk_bf16_f32 v25, v20, v21
	v_lshl_add_u64 v[18:19], s[90:91], 0, v[72:73]
	global_store_dwordx4 v[18:19], v[22:25], off
	v_lshlrev_b32_e32 v20, 16, v24
	v_and_b32_e32 v21, 0xffff0000, v24
	v_lshlrev_b32_e32 v18, 16, v25
	v_and_b32_e32 v19, 0xffff0000, v25
	v_lshlrev_b32_e32 v24, 16, v22
	v_and_b32_e32 v25, 0xffff0000, v22
	v_lshlrev_b32_e32 v22, 16, v23
	v_and_b32_e32 v23, 0xffff0000, v23
	v_lshl_add_u64 v[72:73], s[96:97], 0, v[72:73]
	s_waitcnt vmcnt(2)
	v_pk_add_f32 v[22:23], v[70:71], v[22:23]
	v_pk_add_f32 v[24:25], v[68:69], v[24:25]
	s_waitcnt vmcnt(1)
	v_pk_add_f32 v[18:19], v[100:101], v[18:19]
	v_pk_add_f32 v[20:21], v[98:99], v[20:21]
	v_pk_mul_f32 v[70:71], v[150:151], v[22:23]
	v_pk_mul_f32 v[68:69], v[152:153], v[24:25]
	v_pk_mul_f32 v[98:99], v[154:155], v[18:19]
	v_pk_mul_f32 v[100:101], v[156:157], v[20:21]
	v_cvt_pk_bf16_f32 v68, v68, v69
	v_cvt_pk_bf16_f32 v69, v70, v71
	s_nop 0
	v_cvt_pk_bf16_f32 v70, v100, v101
	v_cvt_pk_bf16_f32 v71, v98, v99
	global_store_dwordx4 v[72:73], v[68:71], off
	global_load_dwordx4 v[68:71], v[190:191], off offset:512 nt
	s_nop 0
	global_load_dwordx4 v[98:101], v[190:191], off offset:528 nt
	v_lshl_add_u64 v[72:73], v[192:193], 0, v[148:149]
	v_lshlrev_b64 v[72:73], 1, v[72:73]
	v_cvt_pk_bf16_f32 v14, v14, v15
	v_cvt_pk_bf16_f32 v15, v16, v17
	v_cvt_pk_bf16_f32 v16, v10, v11
	v_cvt_pk_bf16_f32 v17, v12, v13
	v_lshl_add_u64 v[10:11], s[90:91], 0, v[72:73]
	global_store_dwordx4 v[10:11], v[14:17], off
	v_lshlrev_b32_e32 v12, 16, v16
	v_and_b32_e32 v13, 0xffff0000, v16
	v_lshlrev_b32_e32 v10, 16, v17
	v_and_b32_e32 v11, 0xffff0000, v17
	v_lshlrev_b32_e32 v16, 16, v14
	v_and_b32_e32 v17, 0xffff0000, v14
	v_lshlrev_b32_e32 v14, 16, v15
	v_and_b32_e32 v15, 0xffff0000, v15
	v_lshl_add_u64 v[72:73], s[96:97], 0, v[72:73]
	s_waitcnt vmcnt(2)
	v_pk_add_f32 v[14:15], v[70:71], v[14:15]
	v_pk_add_f32 v[16:17], v[68:69], v[16:17]
	s_waitcnt vmcnt(1)
	v_pk_add_f32 v[10:11], v[100:101], v[10:11]
	v_pk_add_f32 v[12:13], v[98:99], v[12:13]
	v_pk_mul_f32 v[70:71], v[150:151], v[14:15]
	v_pk_mul_f32 v[68:69], v[152:153], v[16:17]
	v_pk_mul_f32 v[98:99], v[154:155], v[10:11]
	v_pk_mul_f32 v[100:101], v[156:157], v[12:13]
	v_cvt_pk_bf16_f32 v68, v68, v69
	v_cvt_pk_bf16_f32 v69, v70, v71
	s_nop 0
	v_cvt_pk_bf16_f32 v70, v100, v101
	v_cvt_pk_bf16_f32 v71, v98, v99
	global_store_dwordx4 v[72:73], v[68:71], off
	global_load_dwordx4 v[68:71], v[194:195], off offset:512 nt
	s_nop 0
	global_load_dwordx4 v[98:101], v[194:195], off offset:528 nt
	v_lshl_add_u64 v[72:73], v[196:197], 0, v[148:149]
	v_lshlrev_b64 v[30:31], 1, v[72:73]
	v_cvt_pk_bf16_f32 v6, v6, v7
	v_cvt_pk_bf16_f32 v7, v8, v9
	v_cvt_pk_bf16_f32 v8, v2, v3
	v_cvt_pk_bf16_f32 v9, v4, v5
	v_lshl_add_u64 v[2:3], s[90:91], 0, v[30:31]
	global_store_dwordx4 v[2:3], v[6:9], off
	v_lshlrev_b32_e32 v4, 16, v8
	v_and_b32_e32 v5, 0xffff0000, v8
	v_lshlrev_b32_e32 v2, 16, v9
	v_and_b32_e32 v3, 0xffff0000, v9
	v_lshlrev_b32_e32 v8, 16, v6
	v_and_b32_e32 v9, 0xffff0000, v6
	v_lshlrev_b32_e32 v6, 16, v7
	v_and_b32_e32 v7, 0xffff0000, v7
	v_lshl_add_u64 v[30:31], s[96:97], 0, v[30:31]
	s_waitcnt vmcnt(2)
	v_pk_add_f32 v[8:9], v[68:69], v[8:9]
	v_pk_add_f32 v[6:7], v[70:71], v[6:7]
	v_pk_mul_f32 v[26:27], v[152:153], v[8:9]
	s_waitcnt vmcnt(1)
	v_pk_add_f32 v[2:3], v[100:101], v[2:3]
	v_pk_add_f32 v[4:5], v[98:99], v[4:5]
	v_pk_mul_f32 v[28:29], v[150:151], v[6:7]
	v_cvt_pk_bf16_f32 v26, v26, v27
	v_pk_mul_f32 v[32:33], v[154:155], v[2:3]
	v_cvt_pk_bf16_f32 v27, v28, v29
	v_pk_mul_f32 v[68:69], v[156:157], v[4:5]
	s_nop 0
	v_cvt_pk_bf16_f32 v28, v68, v69
	v_cvt_pk_bf16_f32 v29, v32, v33
	global_store_dwordx4 v[30:31], v[26:29], off
	s_nop 1
	v_and_b32_e32 v27, 64, v218
	v_xor_b32_e32 v26, 16, v218
	v_add_u32_e32 v27, 64, v27
	v_cmp_lt_i32_e32 vcc, v26, v27
	s_nop 1
	v_cndmask_b32_e32 v26, v218, v26, vcc
	v_lshlrev_b32_e32 v28, 2, v26
	v_xor_b32_e32 v26, 32, v218
	v_cmp_lt_i32_e32 vcc, v26, v27
	s_nop 1
	v_cndmask_b32_e32 v26, v218, v26, vcc
	v_lshlrev_b32_e32 v29, 2, v26
	ds_bpermute_b32 v26, v28, v66
	s_waitcnt lgkmcnt(0)
	v_add_f32_e32 v30, v66, v26
	ds_bpermute_b32 v31, v29, v30
	v_lshl_add_u64 v[26:27], v[146:147], 3, s[42:43]
	s_and_saveexec_b64 s[4:5], s[0:1]
	s_mov_b32 s8, 0x2f800000
	s_mov_b32 s9, 0xcf800000
	s_cbranch_execz .LBB0_558
	s_waitcnt lgkmcnt(0)
	v_add_f32_e32 v30, v30, v31
	v_mul_f32_e32 v30, 0x47800000, v30
	v_rndne_f32_e32 v30, v30
	v_mul_f32_e64 v31, |v30|, s8
	v_floor_f32_e32 v31, v31
	v_fma_f32 v32, v31, s9, |v30|
	v_cvt_u32_f32_e32 v32, v32
	v_cvt_u32_f32_e32 v31, v31
	v_ashrrev_i32_e32 v33, 31, v30
	v_xor_b32_e32 v30, v32, v33
	v_xor_b32_e32 v31, v31, v33
	v_sub_co_u32_e32 v30, vcc, v30, v33
	s_nop 1
	v_subb_co_u32_e32 v31, vcc, v31, v33, vcc
	global_atomic_add_x2 v[26:27], v[30:31], off

; #define PG8_STAGE(bufoff, gbase, voff) do { const char* gb_ = (const char*)(gbase); asm volatile("" : "+s"(gb_)); _Pragma("unroll") for (int _i = 0; _i < 2; ++_i) { unsigned vo_ = (voff)[_i]; asm volatile("" : "+v"(vo_));        \
;         __builtin_amdgcn_global_load_lds((const unsigned*)(gb_ + vo_), (PG8_LAS unsigned*)(lds + (bufoff) + ldsw + _i * 8192), 16, 0, 0); } } while (0)
; #define PG8_LDA(dst, b, h) do { _Pragma("unroll") for (int m = 0; m < 4; ++m) _Pragma("unroll") for (int k = 0; k < 2; ++k) dst[m][k] = *(const PG8_LAS bf16x8*)(lds + PG8_SA(b, h) + aoff + m * 2048 + k * 1024); } while (0)
; #define PG8_LDB(dst, b, h) do { _Pragma("unroll") for (int n = 0; n < 2; ++n) _Pragma("unroll") for (int k = 0; k < 2; ++k) dst[n][k] = *(const PG8_LAS bf16x8*)(lds + PG8_SB(b, h) + boff + n * 2048 + k * 1024); } while (0)
; #define PG8_MMA(ai, bj, At, Bt) do { __builtin_amdgcn_s_setprio(1); _Pragma("unroll") for (int m = 0; m < 4; ++m) _Pragma("unroll") for (int n = 0; n < 2; ++n) _Pragma("unroll") for (int k = 0; k < 2; ++k) \
;         acc[ai][bj][m][n] = __builtin_amdgcn_mfma_f32_16x16x32_bf16(Bt[n][k], At[m][k], acc[ai][bj][m][n], 0, 0, 0); __builtin_amdgcn_s_setprio(0); } while (0)
; #define PG8_WAIT_V(n) asm volatile("s_waitcnt vmcnt(" #n ")" ::: "memory")
; template <class Epi, class Sched, bool ALIGN_EPI = false, bool SP2 = false>
; __device__ __forceinline__ void gemm_phase(PG8_LAS unsigned char* lds, const Gemm g, const Sched& S, const Epi& E) {
;     ...
;             const bool last = (t == nt - 2);
;             const char* a1 = cA + (size_t)(t + 1) * kstep;
;             const char* a2 = last ? nA : cA + (size_t)(t + 2) * kstep; const char* b2 = last ? nB : cB + (size_t)(t + 2) * kstep;
;             const char* a3 = a2 + kstep; const char* b3 = b2 + kstep;
;             if (last && has_next) S.a_ready(nxt);
;             if constexpr (SP2) {
;             PG8_LDB(B0, 0, 0); PG8_LDB(B1, 0, 1); PG8_SCHED; PG8_LDA(At, 0, 0); PG8_STAGE(PG8_SA(1, 1), a1 + hstep, voffA);
;             PG8_WAIT_V(8); PG8_WAIT_L(0); PG8_BAR; PG8_MMA(0, 0, At, B0); PG8_MMA(0, 1, At, B1); PG8_BAR; PG8_SCHED;
;             PG8_LDA(At, 0, 1); PG8_STAGE(PG8_SB(0, 0), b2, voffB); PG8_STAGE(PG8_SB(0, 1), b2 + hstep, voffB); PG8_STAGE(PG8_SA(0, 0), a2, voffA);
;             PG8_WAIT_V(8); PG8_WAIT_L(0); PG8_BAR; PG8_MMA(1, 0, At, B0); PG8_MMA(1, 1, At, B1); PG8_BAR; PG8_SCHED;
.LBB0_634:
	s_add_u32 s16, s14, 0x100
	s_addc_u32 s17, s15, 0
	s_cmp_eq_u32 s53, 28
	s_cselect_b32 s22, s49, s16
	s_cselect_b32 s23, s7, s17
	s_cselect_b32 s20, s50, s51
	s_cselect_b32 s21, s5, s52
	s_add_u32 s18, s22, 0x80
	s_addc_u32 s19, s23, 0
	s_add_i32 s54, 0, 0x10000
	s_add_i32 s55, 0, 0x14000
	ds_read_b128 v[82:85], v244
	ds_read_b128 v[86:89], v244 offset:1024
	ds_read_b128 v[90:93], v244 offset:2048
	ds_read_b128 v[94:97], v244 offset:3072
	ds_read_b128 v[146:149], v244 offset:16384
	ds_read_b128 v[150:153], v244 offset:17408
	ds_read_b128 v[154:157], v244 offset:18432
	ds_read_b128 v[158:161], v244 offset:19456
	s_add_u32 s14, s14, 0x80080
	s_addc_u32 s15, s15, 0
	ds_read_b128 v[178:181], v188
	ds_read_b128 v[190:193], v188 offset:1024
	ds_read_b128 v[194:197], v188 offset:2048
	ds_read_b128 v[198:201], v188 offset:3072
	ds_read_b128 v[202:205], v188 offset:4096
	ds_read_b128 v[206:209], v188 offset:5120
	ds_read_b128 v[210:213], v188 offset:6144
	ds_read_b128 v[220:223], v188 offset:7168
	s_add_i32 m0, s27, 0xc000
	s_nop 0
	global_load_lds_dwordx4 v1, s[14:15]
	s_add_i32 m0, s27, 0xe000
	s_nop 0
	global_load_lds_dwordx4 v164, s[14:15]
	s_waitcnt vmcnt(8)
	s_waitcnt lgkmcnt(0)
	s_barrier
	s_setprio 1
	s_waitcnt lgkmcnt(0)
	v_mfma_f32_16x16x32_bf16 v[142:145], v[82:85], v[178:181], v[142:145]
	v_mfma_f32_16x16x32_bf16 v[142:145], v[86:89], v[190:193], v[142:145]
	v_mfma_f32_16x16x32_bf16 v[138:141], v[90:93], v[178:181], v[138:141]
	v_mfma_f32_16x16x32_bf16 v[138:141], v[94:97], v[190:193], v[138:141]
	v_mfma_f32_16x16x32_bf16 v[134:137], v[146:149], v[178:181], v[134:137]
	v_mfma_f32_16x16x32_bf16 v[134:137], v[150:153], v[190:193], v[134:137]
	v_mfma_f32_16x16x32_bf16 v[130:133], v[154:157], v[178:181], v[130:133]
	v_mfma_f32_16x16x32_bf16 v[130:133], v[158:161], v[190:193], v[130:133]
	v_mfma_f32_16x16x32_bf16 v[126:129], v[82:85], v[194:197], v[126:129]
	v_mfma_f32_16x16x32_bf16 v[126:129], v[86:89], v[198:201], v[126:129]
	v_mfma_f32_16x16x32_bf16 v[122:125], v[90:93], v[194:197], v[122:125]
	v_mfma_f32_16x16x32_bf16 v[122:125], v[94:97], v[198:201], v[122:125]
	v_mfma_f32_16x16x32_bf16 v[118:121], v[146:149], v[194:197], v[118:121]
	v_mfma_f32_16x16x32_bf16 v[118:121], v[150:153], v[198:201], v[118:121]
	v_mfma_f32_16x16x32_bf16 v[114:117], v[154:157], v[194:197], v[114:117]
	v_mfma_f32_16x16x32_bf16 v[114:117], v[158:161], v[198:201], v[114:117]
	v_mfma_f32_16x16x32_bf16 v[110:113], v[82:85], v[202:205], v[110:113]
	v_mfma_f32_16x16x32_bf16 v[110:113], v[86:89], v[206:209], v[110:113]
	v_mfma_f32_16x16x32_bf16 v[106:109], v[90:93], v[202:205], v[106:109]
	v_mfma_f32_16x16x32_bf16 v[106:109], v[94:97], v[206:209], v[106:109]
	v_mfma_f32_16x16x32_bf16 v[102:105], v[146:149], v[202:205], v[102:105]
	v_mfma_f32_16x16x32_bf16 v[102:105], v[150:153], v[206:209], v[102:105]
	v_mfma_f32_16x16x32_bf16 v[98:101], v[154:157], v[202:205], v[98:101]
	v_mfma_f32_16x16x32_bf16 v[98:101], v[158:161], v[206:209], v[98:101]
	v_mfma_f32_16x16x32_bf16 v[78:81], v[82:85], v[210:213], v[78:81]
	v_mfma_f32_16x16x32_bf16 v[78:81], v[86:89], v[220:223], v[78:81]
	v_mfma_f32_16x16x32_bf16 v[74:77], v[90:93], v[210:213], v[74:77]
	v_mfma_f32_16x16x32_bf16 v[74:77], v[94:97], v[220:223], v[74:77]
	v_mfma_f32_16x16x32_bf16 v[70:73], v[146:149], v[210:213], v[70:73]
	v_mfma_f32_16x16x32_bf16 v[70:73], v[150:153], v[220:223], v[70:73]
	v_mfma_f32_16x16x32_bf16 v[66:69], v[154:157], v[210:213], v[66:69]
	v_mfma_f32_16x16x32_bf16 v[66:69], v[158:161], v[220:223], v[66:69]
	s_setprio 0
	s_barrier
	s_mov_b64 s[14:15], s[20:21]
	s_add_i32 s54, s54, s26
	ds_read_b128 v[178:181], v188 offset:16384
	ds_read_b128 v[190:193], v188 offset:17408
	ds_read_b128 v[194:197], v188 offset:18432
	ds_read_b128 v[198:201], v188 offset:19456
	ds_read_b128 v[202:205], v188 offset:20480
	ds_read_b128 v[206:209], v188 offset:21504
	ds_read_b128 v[210:213], v188 offset:22528
	ds_read_b128 v[220:223], v188 offset:23552
	s_mov_b32 m0, s54
	s_nop 0
	global_load_lds_dwordx4 v162, s[14:15]
	s_add_i32 m0, s54, 0x2000
	s_nop 0
	global_load_lds_dwordx4 v184, s[14:15]
	s_add_u32 s14, s20, 0x80000
	s_addc_u32 s15, s21, 0
	s_add_i32 s54, s55, s26
	s_mov_b32 m0, s54
	s_nop 0
	global_load_lds_dwordx4 v162, s[14:15]
	s_add_i32 m0, s54, 0x2000
	s_nop 0
	global_load_lds_dwordx4 v184, s[14:15]
	s_mov_b64 s[14:15], s[22:23]
	s_mov_b32 m0, s27
	s_nop 0
	global_load_lds_dwordx4 v1, s[14:15]
	s_mov_b32 m0, s28
	s_nop 0
	global_load_lds_dwordx4 v164, s[14:15]
	s_waitcnt vmcnt(8)
	s_waitcnt lgkmcnt(0)
	s_barrier
; #define PG8_STAGE(bufoff, gbase, voff) do { const char* gb_ = (const char*)(gbase); asm volatile("" : "+s"(gb_)); _Pragma("unroll") for (int _i = 0; _i < 2; ++_i) { unsigned vo_ = (voff)[_i]; asm volatile("" : "+v"(vo_));        \
;         __builtin_amdgcn_global_load_lds((const unsigned*)(gb_ + vo_), (PG8_LAS unsigned*)(lds + (bufoff) + ldsw + _i * 8192), 16, 0, 0); } } while (0)
; #define PG8_LDA(dst, b, h) do { _Pragma("unroll") for (int m = 0; m < 4; ++m) _Pragma("unroll") for (int k = 0; k < 2; ++k) dst[m][k] = *(const PG8_LAS bf16x8*)(lds + PG8_SA(b, h) + aoff + m * 2048 + k * 1024); } while (0)
; #define PG8_LDB(dst, b, h) do { _Pragma("unroll") for (int n = 0; n < 2; ++n) _Pragma("unroll") for (int k = 0; k < 2; ++k) dst[n][k] = *(const PG8_LAS bf16x8*)(lds + PG8_SB(b, h) + boff + n * 2048 + k * 1024); } while (0)
; #define PG8_MMA(ai, bj, At, Bt) do { __builtin_amdgcn_s_setprio(1); _Pragma("unroll") for (int m = 0; m < 4; ++m) _Pragma("unroll") for (int n = 0; n < 2; ++n) _Pragma("unroll") for (int k = 0; k < 2; ++k) \
;         acc[ai][bj][m][n] = __builtin_amdgcn_mfma_f32_16x16x32_bf16(Bt[n][k], At[m][k], acc[ai][bj][m][n], 0, 0, 0); __builtin_amdgcn_s_setprio(0); } while (0)
; #define PG8_WAIT_V(n) asm volatile("s_waitcnt vmcnt(" #n ")" ::: "memory")
; #define PG8_WAIT_L(n) asm volatile("s_waitcnt lgkmcnt(" #n ")" ::: "memory")
; #define PG8_BAR __builtin_amdgcn_s_barrier()
; #define PG8_SCHED __builtin_amdgcn_sched_barrier(0)
; template <class Epi, class Sched, bool ALIGN_EPI = false, bool SP2 = false>
; __device__ __forceinline__ void gemm_phase(PG8_LAS unsigned char* lds, const Gemm g, const Sched& S, const Epi& E) {
;     ...
;             PG8_WAIT_V(8); PG8_WAIT_L(0); PG8_BAR; PG8_MMA(1, 0, At, B0); PG8_MMA(1, 1, At, B1); PG8_BAR; PG8_SCHED;
;             PG8_LDB(B0, 1, 0); PG8_LDB(B1, 1, 1); PG8_SCHED; PG8_LDA(At, 1, 0); PG8_STAGE(PG8_SA(0, 1), a2 + hstep, voffA);
;             PG8_WAIT_V(8); PG8_WAIT_L(0); PG8_BAR; PG8_MMA(0, 0, At, B0); PG8_MMA(0, 1, At, B1); PG8_BAR; PG8_SCHED;
	s_setprio 1
	s_waitcnt lgkmcnt(0)
	v_mfma_f32_16x16x32_bf16 v[62:65], v[82:85], v[178:181], v[62:65]
	v_mfma_f32_16x16x32_bf16 v[62:65], v[86:89], v[190:193], v[62:65]
	v_mfma_f32_16x16x32_bf16 v[58:61], v[90:93], v[178:181], v[58:61]
	v_mfma_f32_16x16x32_bf16 v[58:61], v[94:97], v[190:193], v[58:61]
	v_mfma_f32_16x16x32_bf16 v[54:57], v[146:149], v[178:181], v[54:57]
	v_mfma_f32_16x16x32_bf16 v[54:57], v[150:153], v[190:193], v[54:57]
	v_mfma_f32_16x16x32_bf16 v[50:53], v[154:157], v[178:181], v[50:53]
	v_mfma_f32_16x16x32_bf16 v[50:53], v[158:161], v[190:193], v[50:53]
	v_mfma_f32_16x16x32_bf16 v[46:49], v[82:85], v[194:197], v[46:49]
	v_mfma_f32_16x16x32_bf16 v[46:49], v[86:89], v[198:201], v[46:49]
	v_mfma_f32_16x16x32_bf16 v[42:45], v[90:93], v[194:197], v[42:45]
	v_mfma_f32_16x16x32_bf16 v[42:45], v[94:97], v[198:201], v[42:45]
	v_mfma_f32_16x16x32_bf16 v[38:41], v[146:149], v[194:197], v[38:41]
	v_mfma_f32_16x16x32_bf16 v[38:41], v[150:153], v[198:201], v[38:41]
	v_mfma_f32_16x16x32_bf16 v[34:37], v[154:157], v[194:197], v[34:37]
	v_mfma_f32_16x16x32_bf16 v[34:37], v[158:161], v[198:201], v[34:37]
	v_mfma_f32_16x16x32_bf16 v[30:33], v[82:85], v[202:205], v[30:33]
	v_mfma_f32_16x16x32_bf16 v[30:33], v[86:89], v[206:209], v[30:33]
	v_mfma_f32_16x16x32_bf16 v[26:29], v[90:93], v[202:205], v[26:29]
	v_mfma_f32_16x16x32_bf16 v[26:29], v[94:97], v[206:209], v[26:29]
	v_mfma_f32_16x16x32_bf16 v[22:25], v[146:149], v[202:205], v[22:25]
	v_mfma_f32_16x16x32_bf16 v[22:25], v[150:153], v[206:209], v[22:25]
	v_mfma_f32_16x16x32_bf16 v[18:21], v[154:157], v[202:205], v[18:21]
	v_mfma_f32_16x16x32_bf16 v[18:21], v[158:161], v[206:209], v[18:21]
	v_mfma_f32_16x16x32_bf16 v[14:17], v[82:85], v[210:213], v[14:17]
	v_mfma_f32_16x16x32_bf16 v[14:17], v[86:89], v[220:223], v[14:17]
	v_mfma_f32_16x16x32_bf16 v[10:13], v[90:93], v[210:213], v[10:13]
	v_mfma_f32_16x16x32_bf16 v[10:13], v[94:97], v[220:223], v[10:13]
	v_mfma_f32_16x16x32_bf16 v[6:9], v[146:149], v[210:213], v[6:9]
	v_mfma_f32_16x16x32_bf16 v[6:9], v[150:153], v[220:223], v[6:9]
	v_mfma_f32_16x16x32_bf16 v[2:5], v[154:157], v[210:213], v[2:5]
	v_mfma_f32_16x16x32_bf16 v[2:5], v[158:161], v[220:223], v[2:5]
	s_setprio 0
	s_barrier
	s_add_i32 s54, 0, 0x18000
	s_add_i32 s55, 0, 0x1c000
	ds_read_b128 v[82:85], v244 offset:32768
	ds_read_b128 v[86:89], v244 offset:33792
	ds_read_b128 v[90:93], v244 offset:34816
	ds_read_b128 v[94:97], v244 offset:35840
	ds_read_b128 v[146:149], v244 offset:49152
	ds_read_b128 v[150:153], v244 offset:50176
	ds_read_b128 v[154:157], v244 offset:51200
	ds_read_b128 v[158:161], v244 offset:52224
	s_add_u32 s14, s22, 0x80000
	s_addc_u32 s15, s23, 0
	s_mov_b32 m0, s29
	ds_read_b128 v[178:181], v188 offset:32768
	ds_read_b128 v[190:193], v188 offset:33792
	ds_read_b128 v[194:197], v188 offset:34816
	ds_read_b128 v[198:201], v188 offset:35840
	ds_read_b128 v[202:205], v188 offset:36864
	ds_read_b128 v[206:209], v188 offset:37888
	ds_read_b128 v[210:213], v188 offset:38912
	ds_read_b128 v[220:223], v188 offset:39936
	s_nop 0
	global_load_lds_dwordx4 v1, s[14:15]
	s_mov_b32 m0, s33
	s_nop 0
	global_load_lds_dwordx4 v164, s[14:15]
	s_waitcnt vmcnt(8)
	s_waitcnt lgkmcnt(0)
	s_barrier
	s_setprio 1
	s_waitcnt lgkmcnt(0)
	v_mfma_f32_16x16x32_bf16 v[142:145], v[82:85], v[178:181], v[142:145]
	v_mfma_f32_16x16x32_bf16 v[142:145], v[86:89], v[190:193], v[142:145]
	v_mfma_f32_16x16x32_bf16 v[138:141], v[90:93], v[178:181], v[138:141]
	v_mfma_f32_16x16x32_bf16 v[138:141], v[94:97], v[190:193], v[138:141]
	v_mfma_f32_16x16x32_bf16 v[134:137], v[146:149], v[178:181], v[134:137]
	v_mfma_f32_16x16x32_bf16 v[134:137], v[150:153], v[190:193], v[134:137]
	v_mfma_f32_16x16x32_bf16 v[130:133], v[154:157], v[178:181], v[130:133]
	v_mfma_f32_16x16x32_bf16 v[130:133], v[158:161], v[190:193], v[130:133]
	v_mfma_f32_16x16x32_bf16 v[126:129], v[82:85], v[194:197], v[126:129]
	v_mfma_f32_16x16x32_bf16 v[126:129], v[86:89], v[198:201], v[126:129]
	v_mfma_f32_16x16x32_bf16 v[122:125], v[90:93], v[194:197], v[122:125]
	v_mfma_f32_16x16x32_bf16 v[122:125], v[94:97], v[198:201], v[122:125]
	v_mfma_f32_16x16x32_bf16 v[118:121], v[146:149], v[194:197], v[118:121]
	v_mfma_f32_16x16x32_bf16 v[118:121], v[150:153], v[198:201], v[118:121]
	v_mfma_f32_16x16x32_bf16 v[114:117], v[154:157], v[194:197], v[114:117]
	v_mfma_f32_16x16x32_bf16 v[114:117], v[158:161], v[198:201], v[114:117]
	v_mfma_f32_16x16x32_bf16 v[110:113], v[82:85], v[202:205], v[110:113]
	v_mfma_f32_16x16x32_bf16 v[110:113], v[86:89], v[206:209], v[110:113]
	v_mfma_f32_16x16x32_bf16 v[106:109], v[90:93], v[202:205], v[106:109]
	v_mfma_f32_16x16x32_bf16 v[106:109], v[94:97], v[206:209], v[106:109]
	v_mfma_f32_16x16x32_bf16 v[102:105], v[146:149], v[202:205], v[102:105]
	v_mfma_f32_16x16x32_bf16 v[102:105], v[150:153], v[206:209], v[102:105]
	v_mfma_f32_16x16x32_bf16 v[98:101], v[154:157], v[202:205], v[98:101]
	v_mfma_f32_16x16x32_bf16 v[98:101], v[158:161], v[206:209], v[98:101]
	v_mfma_f32_16x16x32_bf16 v[78:81], v[82:85], v[210:213], v[78:81]
	v_mfma_f32_16x16x32_bf16 v[78:81], v[86:89], v[220:223], v[78:81]
	v_mfma_f32_16x16x32_bf16 v[74:77], v[90:93], v[210:213], v[74:77]
	v_mfma_f32_16x16x32_bf16 v[74:77], v[94:97], v[220:223], v[74:77]
	v_mfma_f32_16x16x32_bf16 v[70:73], v[146:149], v[210:213], v[70:73]
	v_mfma_f32_16x16x32_bf16 v[70:73], v[150:153], v[220:223], v[70:73]
	v_mfma_f32_16x16x32_bf16 v[66:69], v[154:157], v[210:213], v[66:69]
	v_mfma_f32_16x16x32_bf16 v[66:69], v[158:161], v[220:223], v[66:69]
	s_setprio 0
	s_barrier
; #define PG8_STAGE(bufoff, gbase, voff) do { const char* gb_ = (const char*)(gbase); asm volatile("" : "+s"(gb_)); _Pragma("unroll") for (int _i = 0; _i < 2; ++_i) { unsigned vo_ = (voff)[_i]; asm volatile("" : "+v"(vo_));        \
;         __builtin_amdgcn_global_load_lds((const unsigned*)(gb_ + vo_), (PG8_LAS unsigned*)(lds + (bufoff) + ldsw + _i * 8192), 16, 0, 0); } } while (0)
; #define PG8_LDA(dst, b, h) do { _Pragma("unroll") for (int m = 0; m < 4; ++m) _Pragma("unroll") for (int k = 0; k < 2; ++k) dst[m][k] = *(const PG8_LAS bf16x8*)(lds + PG8_SA(b, h) + aoff + m * 2048 + k * 1024); } while (0)
; #define PG8_MMA(ai, bj, At, Bt) do { __builtin_amdgcn_s_setprio(1); _Pragma("unroll") for (int m = 0; m < 4; ++m) _Pragma("unroll") for (int n = 0; n < 2; ++n) _Pragma("unroll") for (int k = 0; k < 2; ++k) \
;         acc[ai][bj][m][n] = __builtin_amdgcn_mfma_f32_16x16x32_bf16(Bt[n][k], At[m][k], acc[ai][bj][m][n], 0, 0, 0); __builtin_amdgcn_s_setprio(0); } while (0)
; #define PG8_WAIT_V(n) asm volatile("s_waitcnt vmcnt(" #n ")" ::: "memory")
; #define PG8_WAIT_L(n) asm volatile("s_waitcnt lgkmcnt(" #n ")" ::: "memory")
; #define PG8_BAR __builtin_amdgcn_s_barrier()
; #define PG8_SCHED __builtin_amdgcn_sched_barrier(0)
; template <class Epi, class Sched, bool ALIGN_EPI = false, bool SP2 = false>
; __device__ __forceinline__ void gemm_phase(PG8_LAS unsigned char* lds, const Gemm g, const Sched& S, const Epi& E) {
;     ...
;             PG8_LDA(At, 1, 1); PG8_STAGE(PG8_SB(1, 0), b3, voffB); PG8_STAGE(PG8_SB(1, 1), b3 + hstep, voffB); PG8_STAGE(PG8_SA(1, 0), a3, voffA);
;             PG8_WAIT_V(8); PG8_WAIT_L(0); PG8_BAR; PG8_MMA(1, 0, At, B0); PG8_MMA(1, 1, At, B1); PG8_BAR; PG8_SCHED;
;     ...
;         if constexpr (ALIGN_EPI) { if (wr == 0) PG8_BAR; }
	s_add_u32 s14, s20, 0x80
	s_addc_u32 s15, s21, 0
	s_add_i32 s22, s54, s26
	ds_read_b128 v[178:181], v188 offset:49152
	ds_read_b128 v[190:193], v188 offset:50176
	ds_read_b128 v[194:197], v188 offset:51200
	ds_read_b128 v[198:201], v188 offset:52224
	ds_read_b128 v[202:205], v188 offset:53248
	ds_read_b128 v[206:209], v188 offset:54272
	ds_read_b128 v[210:213], v188 offset:55296
	ds_read_b128 v[220:223], v188 offset:56320
	s_mov_b32 m0, s22
	s_nop 0
	global_load_lds_dwordx4 v162, s[14:15]
	s_add_i32 m0, s22, 0x2000
	s_nop 0
	global_load_lds_dwordx4 v184, s[14:15]
	s_add_u32 s14, s20, 0x80080
	s_addc_u32 s15, s21, 0
	s_add_i32 s20, s55, s26
	s_mov_b32 m0, s20
	s_nop 0
	global_load_lds_dwordx4 v162, s[14:15]
	s_add_i32 m0, s20, 0x2000
	s_nop 0
	global_load_lds_dwordx4 v184, s[14:15]
	s_mov_b32 m0, s38
	s_nop 0
	global_load_lds_dwordx4 v1, s[18:19]
	s_mov_b32 m0, s39
	s_nop 0
	global_load_lds_dwordx4 v164, s[18:19]
	s_waitcnt vmcnt(8)
	s_waitcnt lgkmcnt(0)
	s_barrier
	s_setprio 1
	s_waitcnt lgkmcnt(0)
	v_mfma_f32_16x16x32_bf16 v[62:65], v[82:85], v[178:181], v[62:65]
	v_mfma_f32_16x16x32_bf16 v[62:65], v[86:89], v[190:193], v[62:65]
	v_mfma_f32_16x16x32_bf16 v[58:61], v[90:93], v[178:181], v[58:61]
	v_mfma_f32_16x16x32_bf16 v[58:61], v[94:97], v[190:193], v[58:61]
	v_mfma_f32_16x16x32_bf16 v[54:57], v[146:149], v[178:181], v[54:57]
	v_mfma_f32_16x16x32_bf16 v[54:57], v[150:153], v[190:193], v[54:57]
	v_mfma_f32_16x16x32_bf16 v[50:53], v[154:157], v[178:181], v[50:53]
	v_mfma_f32_16x16x32_bf16 v[50:53], v[158:161], v[190:193], v[50:53]
	v_mfma_f32_16x16x32_bf16 v[46:49], v[82:85], v[194:197], v[46:49]
	v_mfma_f32_16x16x32_bf16 v[46:49], v[86:89], v[198:201], v[46:49]
	v_mfma_f32_16x16x32_bf16 v[42:45], v[90:93], v[194:197], v[42:45]
	v_mfma_f32_16x16x32_bf16 v[42:45], v[94:97], v[198:201], v[42:45]
	v_mfma_f32_16x16x32_bf16 v[38:41], v[146:149], v[194:197], v[38:41]
	v_mfma_f32_16x16x32_bf16 v[38:41], v[150:153], v[198:201], v[38:41]
	v_mfma_f32_16x16x32_bf16 v[34:37], v[154:157], v[194:197], v[34:37]
	v_mfma_f32_16x16x32_bf16 v[34:37], v[158:161], v[198:201], v[34:37]
	v_mfma_f32_16x16x32_bf16 v[30:33], v[82:85], v[202:205], v[30:33]
	v_mfma_f32_16x16x32_bf16 v[30:33], v[86:89], v[206:209], v[30:33]
	v_mfma_f32_16x16x32_bf16 v[26:29], v[90:93], v[202:205], v[26:29]
	v_mfma_f32_16x16x32_bf16 v[26:29], v[94:97], v[206:209], v[26:29]
	v_mfma_f32_16x16x32_bf16 v[22:25], v[146:149], v[202:205], v[22:25]
	v_mfma_f32_16x16x32_bf16 v[22:25], v[150:153], v[206:209], v[22:25]
	v_mfma_f32_16x16x32_bf16 v[18:21], v[154:157], v[202:205], v[18:21]
	v_mfma_f32_16x16x32_bf16 v[18:21], v[158:161], v[206:209], v[18:21]
	v_mfma_f32_16x16x32_bf16 v[14:17], v[82:85], v[210:213], v[14:17]
	v_mfma_f32_16x16x32_bf16 v[14:17], v[86:89], v[220:223], v[14:17]
	v_mfma_f32_16x16x32_bf16 v[10:13], v[90:93], v[210:213], v[10:13]
	v_mfma_f32_16x16x32_bf16 v[10:13], v[94:97], v[220:223], v[10:13]
	v_mfma_f32_16x16x32_bf16 v[6:9], v[146:149], v[210:213], v[6:9]
	v_mfma_f32_16x16x32_bf16 v[6:9], v[150:153], v[220:223], v[6:9]
	v_mfma_f32_16x16x32_bf16 v[2:5], v[154:157], v[210:213], v[2:5]
	v_mfma_f32_16x16x32_bf16 v[2:5], v[158:161], v[220:223], v[2:5]
	s_setprio 0
	s_barrier
	s_add_i32 s53, s53, 2
	s_add_u32 s51, s51, 0x100
	s_addc_u32 s52, s52, 0
	s_cmp_gt_u32 s53, 29
	s_mov_b64 s[14:15], s[16:17]
	s_cbranch_scc0 .LBB0_634
	s_and_b64 vcc, exec, s[2:3]
	s_cbranch_vccz .LBB0_637
	s_barrier

; #define PG8_STAGE(bufoff, gbase, voff) do { const char* gb_ = (const char*)(gbase); asm volatile("" : "+s"(gb_)); _Pragma("unroll") for (int _i = 0; _i < 2; ++_i) { unsigned vo_ = (voff)[_i]; asm volatile("" : "+v"(vo_));        \
;         __builtin_amdgcn_global_load_lds((const unsigned*)(gb_ + vo_), (PG8_LAS unsigned*)(lds + (bufoff) + ldsw + _i * 8192), 16, 0, 0); } } while (0)
; #define PG8_LDA(dst, b, h) do { _Pragma("unroll") for (int m = 0; m < 4; ++m) _Pragma("unroll") for (int k = 0; k < 2; ++k) dst[m][k] = *(const PG8_LAS bf16x8*)(lds + PG8_SA(b, h) + aoff + m * 2048 + k * 1024); } while (0)
; #define PG8_LDB(dst, b, h) do { _Pragma("unroll") for (int n = 0; n < 2; ++n) _Pragma("unroll") for (int k = 0; k < 2; ++k) dst[n][k] = *(const PG8_LAS bf16x8*)(lds + PG8_SB(b, h) + boff + n * 2048 + k * 1024); } while (0)
; #define PG8_MMA(ai, bj, At, Bt) do { __builtin_amdgcn_s_setprio(1); _Pragma("unroll") for (int m = 0; m < 4; ++m) _Pragma("unroll") for (int n = 0; n < 2; ++n) _Pragma("unroll") for (int k = 0; k < 2; ++k) \
;         acc[ai][bj][m][n] = __builtin_amdgcn_mfma_f32_16x16x32_bf16(Bt[n][k], At[m][k], acc[ai][bj][m][n], 0, 0, 0); __builtin_amdgcn_s_setprio(0); } while (0)
; #define PG8_WAIT_V(n) asm volatile("s_waitcnt vmcnt(" #n ")" ::: "memory")
; template <class Epi, class Sched, bool ALIGN_EPI = false, bool SP2 = false>
; __device__ __forceinline__ void gemm_phase(PG8_LAS unsigned char* lds, const Gemm g, const Sched& S, const Epi& E) {
;     ...
;             const bool last = (t == nt - 2);
;             const char* a1 = cA + (size_t)(t + 1) * kstep;
;             const char* a2 = last ? nA : cA + (size_t)(t + 2) * kstep; const char* b2 = last ? nB : cB + (size_t)(t + 2) * kstep;
;             const char* a3 = a2 + kstep; const char* b3 = b2 + kstep;
;             if (last && has_next) S.a_ready(nxt);
;             if constexpr (SP2) {
;             PG8_LDB(B0, 0, 0); PG8_LDB(B1, 0, 1); PG8_SCHED; PG8_LDA(At, 0, 0); PG8_STAGE(PG8_SA(1, 1), a1 + hstep, voffA);
;             PG8_WAIT_V(8); PG8_WAIT_L(0); PG8_BAR; PG8_MMA(0, 0, At, B0); PG8_MMA(0, 1, At, B1); PG8_BAR; PG8_SCHED;
;             PG8_LDA(At, 0, 1); PG8_STAGE(PG8_SB(0, 0), b2, voffB); PG8_STAGE(PG8_SB(0, 1), b2 + hstep, voffB); PG8_STAGE(PG8_SA(0, 0), a2, voffA);
;             PG8_WAIT_V(8); PG8_WAIT_L(0); PG8_BAR; PG8_MMA(1, 0, At, B0); PG8_MMA(1, 1, At, B1); PG8_BAR; PG8_SCHED;
.LBB0_707:
	s_add_u32 s2, s4, 0x100
	s_addc_u32 s3, s5, 0
	s_cmpk_eq_i32 s35, 0x54
	s_cselect_b32 s10, s52, s2
	s_cselect_b32 s11, s53, s3
	s_cselect_b32 s8, s42, s31
	s_cselect_b32 s9, s43, s34
	s_add_u32 s6, s10, 0x80
	s_addc_u32 s7, s11, 0
	s_add_i32 s38, 0, 0x10000
	s_add_i32 s39, 0, 0x14000
	ds_read_b128 v[34:37], v244
	ds_read_b128 v[38:41], v244 offset:1024
	ds_read_b128 v[98:101], v244 offset:2048
	ds_read_b128 v[102:105], v244 offset:3072
	ds_read_b128 v[146:149], v244 offset:16384
	ds_read_b128 v[150:153], v244 offset:17408
	ds_read_b128 v[154:157], v244 offset:18432
	ds_read_b128 v[158:161], v244 offset:19456
	s_add_u32 s4, s4, 0x160080
	s_addc_u32 s5, s5, 0
	ds_read_b128 v[178:181], v194
	ds_read_b128 v[182:185], v194 offset:1024
	ds_read_b128 v[186:189], v194 offset:2048
	ds_read_b128 v[196:199], v194 offset:3072
	ds_read_b128 v[200:203], v194 offset:4096
	ds_read_b128 v[204:207], v194 offset:5120
	ds_read_b128 v[208:211], v194 offset:6144
	ds_read_b128 v[212:215], v194 offset:7168
	s_add_i32 m0, s16, 0xc000
	s_nop 0
	global_load_lds_dwordx4 v1, s[4:5]
	s_add_i32 m0, s16, 0xe000
	s_nop 0
	global_load_lds_dwordx4 v164, s[4:5]
	s_waitcnt vmcnt(8)
	s_waitcnt lgkmcnt(0)
	s_barrier
	s_setprio 1
	s_waitcnt lgkmcnt(0)
	v_mfma_f32_16x16x32_bf16 v[142:145], v[34:37], v[178:181], v[142:145]
	v_mfma_f32_16x16x32_bf16 v[142:145], v[38:41], v[182:185], v[142:145]
	v_mfma_f32_16x16x32_bf16 v[138:141], v[98:101], v[178:181], v[138:141]
	v_mfma_f32_16x16x32_bf16 v[138:141], v[102:105], v[182:185], v[138:141]
	v_mfma_f32_16x16x32_bf16 v[70:73], v[146:149], v[178:181], v[70:73]
	v_mfma_f32_16x16x32_bf16 v[70:73], v[150:153], v[182:185], v[70:73]
	v_mfma_f32_16x16x32_bf16 v[66:69], v[154:157], v[178:181], v[66:69]
	v_mfma_f32_16x16x32_bf16 v[66:69], v[158:161], v[182:185], v[66:69]
	v_mfma_f32_16x16x32_bf16 v[134:137], v[34:37], v[186:189], v[134:137]
	v_mfma_f32_16x16x32_bf16 v[134:137], v[38:41], v[196:199], v[134:137]
	v_mfma_f32_16x16x32_bf16 v[130:133], v[98:101], v[186:189], v[130:133]
	v_mfma_f32_16x16x32_bf16 v[130:133], v[102:105], v[196:199], v[130:133]
	v_mfma_f32_16x16x32_bf16 v[62:65], v[146:149], v[186:189], v[62:65]
	v_mfma_f32_16x16x32_bf16 v[62:65], v[150:153], v[196:199], v[62:65]
	v_mfma_f32_16x16x32_bf16 v[58:61], v[154:157], v[186:189], v[58:61]
	v_mfma_f32_16x16x32_bf16 v[58:61], v[158:161], v[196:199], v[58:61]
	v_mfma_f32_16x16x32_bf16 v[126:129], v[34:37], v[200:203], v[126:129]
	v_mfma_f32_16x16x32_bf16 v[126:129], v[38:41], v[204:207], v[126:129]
	v_mfma_f32_16x16x32_bf16 v[122:125], v[98:101], v[200:203], v[122:125]
	v_mfma_f32_16x16x32_bf16 v[122:125], v[102:105], v[204:207], v[122:125]
	v_mfma_f32_16x16x32_bf16 v[54:57], v[146:149], v[200:203], v[54:57]
	v_mfma_f32_16x16x32_bf16 v[54:57], v[150:153], v[204:207], v[54:57]
	v_mfma_f32_16x16x32_bf16 v[50:53], v[154:157], v[200:203], v[50:53]
	v_mfma_f32_16x16x32_bf16 v[50:53], v[158:161], v[204:207], v[50:53]
	v_mfma_f32_16x16x32_bf16 v[118:121], v[34:37], v[208:211], v[118:121]
	v_mfma_f32_16x16x32_bf16 v[118:121], v[38:41], v[212:215], v[118:121]
	v_mfma_f32_16x16x32_bf16 v[114:117], v[98:101], v[208:211], v[114:117]
	v_mfma_f32_16x16x32_bf16 v[114:117], v[102:105], v[212:215], v[114:117]
	v_mfma_f32_16x16x32_bf16 v[46:49], v[146:149], v[208:211], v[46:49]
	v_mfma_f32_16x16x32_bf16 v[46:49], v[150:153], v[212:215], v[46:49]
	v_mfma_f32_16x16x32_bf16 v[42:45], v[154:157], v[208:211], v[42:45]
	v_mfma_f32_16x16x32_bf16 v[42:45], v[158:161], v[212:215], v[42:45]
	s_setprio 0
	s_barrier
	s_mov_b64 s[4:5], s[8:9]
	s_add_i32 s38, s38, s15
	ds_read_b128 v[178:181], v194 offset:16384
	ds_read_b128 v[182:185], v194 offset:17408
	ds_read_b128 v[186:189], v194 offset:18432
	ds_read_b128 v[196:199], v194 offset:19456
	ds_read_b128 v[200:203], v194 offset:20480
	ds_read_b128 v[204:207], v194 offset:21504
	ds_read_b128 v[208:211], v194 offset:22528
	ds_read_b128 v[212:215], v194 offset:23552
	s_mov_b32 m0, s38
	s_nop 0
	global_load_lds_dwordx4 v162, s[4:5]
	s_add_i32 m0, s38, 0x2000
	s_nop 0
	global_load_lds_dwordx4 v190, s[4:5]
	s_add_u32 s4, s8, 0x160000
	s_addc_u32 s5, s9, 0
	s_add_i32 s38, s39, s15
	s_mov_b32 m0, s38
	s_nop 0
	global_load_lds_dwordx4 v162, s[4:5]
	s_add_i32 m0, s38, 0x2000
	s_nop 0
	global_load_lds_dwordx4 v190, s[4:5]
	s_mov_b64 s[4:5], s[10:11]
	s_mov_b32 m0, s16
	s_nop 0
	global_load_lds_dwordx4 v1, s[4:5]
	s_mov_b32 m0, s17
	s_nop 0
	global_load_lds_dwordx4 v164, s[4:5]
	s_waitcnt vmcnt(8)
	s_waitcnt lgkmcnt(0)
	s_barrier
	s_setprio 1
	s_waitcnt lgkmcnt(0)
	v_mfma_f32_16x16x32_bf16 v[110:113], v[34:37], v[178:181], v[110:113]
	v_mfma_f32_16x16x32_bf16 v[110:113], v[38:41], v[182:185], v[110:113]
	v_mfma_f32_16x16x32_bf16 v[106:109], v[98:101], v[178:181], v[106:109]
	v_mfma_f32_16x16x32_bf16 v[106:109], v[102:105], v[182:185], v[106:109]
	v_mfma_f32_16x16x32_bf16 v[30:33], v[146:149], v[178:181], v[30:33]
	v_mfma_f32_16x16x32_bf16 v[30:33], v[150:153], v[182:185], v[30:33]
	v_mfma_f32_16x16x32_bf16 v[26:29], v[154:157], v[178:181], v[26:29]
	v_mfma_f32_16x16x32_bf16 v[26:29], v[158:161], v[182:185], v[26:29]
	v_mfma_f32_16x16x32_bf16 v[94:97], v[34:37], v[186:189], v[94:97]
	v_mfma_f32_16x16x32_bf16 v[94:97], v[38:41], v[196:199], v[94:97]
	v_mfma_f32_16x16x32_bf16 v[90:93], v[98:101], v[186:189], v[90:93]
	v_mfma_f32_16x16x32_bf16 v[90:93], v[102:105], v[196:199], v[90:93]
	v_mfma_f32_16x16x32_bf16 v[22:25], v[146:149], v[186:189], v[22:25]
	v_mfma_f32_16x16x32_bf16 v[22:25], v[150:153], v[196:199], v[22:25]
	v_mfma_f32_16x16x32_bf16 v[18:21], v[154:157], v[186:189], v[18:21]
	v_mfma_f32_16x16x32_bf16 v[18:21], v[158:161], v[196:199], v[18:21]
	v_mfma_f32_16x16x32_bf16 v[86:89], v[34:37], v[200:203], v[86:89]
	v_mfma_f32_16x16x32_bf16 v[86:89], v[38:41], v[204:207], v[86:89]
	v_mfma_f32_16x16x32_bf16 v[82:85], v[98:101], v[200:203], v[82:85]
	v_mfma_f32_16x16x32_bf16 v[82:85], v[102:105], v[204:207], v[82:85]
	v_mfma_f32_16x16x32_bf16 v[14:17], v[146:149], v[200:203], v[14:17]
	v_mfma_f32_16x16x32_bf16 v[14:17], v[150:153], v[204:207], v[14:17]
	v_mfma_f32_16x16x32_bf16 v[10:13], v[154:157], v[200:203], v[10:13]
	v_mfma_f32_16x16x32_bf16 v[10:13], v[158:161], v[204:207], v[10:13]
	v_mfma_f32_16x16x32_bf16 v[34:37], v[34:37], v[208:211], v[78:81]
	v_mfma_f32_16x16x32_bf16 v[34:37], v[38:41], v[212:215], v[34:37]
	v_mfma_f32_16x16x32_bf16 v[38:41], v[98:101], v[208:211], v[74:77]
	v_mfma_f32_16x16x32_bf16 v[38:41], v[102:105], v[212:215], v[38:41]
	v_mfma_f32_16x16x32_bf16 v[6:9], v[146:149], v[208:211], v[6:9]
	v_mfma_f32_16x16x32_bf16 v[6:9], v[150:153], v[212:215], v[6:9]
	v_mfma_f32_16x16x32_bf16 v[2:5], v[154:157], v[208:211], v[2:5]
	v_mfma_f32_16x16x32_bf16 v[2:5], v[158:161], v[212:215], v[2:5]
	s_setprio 0
	s_barrier
; #define PG8_STAGE(bufoff, gbase, voff) do { const char* gb_ = (const char*)(gbase); asm volatile("" : "+s"(gb_)); _Pragma("unroll") for (int _i = 0; _i < 2; ++_i) { unsigned vo_ = (voff)[_i]; asm volatile("" : "+v"(vo_));        \
;         __builtin_amdgcn_global_load_lds((const unsigned*)(gb_ + vo_), (PG8_LAS unsigned*)(lds + (bufoff) + ldsw + _i * 8192), 16, 0, 0); } } while (0)
; #define PG8_LDA(dst, b, h) do { _Pragma("unroll") for (int m = 0; m < 4; ++m) _Pragma("unroll") for (int k = 0; k < 2; ++k) dst[m][k] = *(const PG8_LAS bf16x8*)(lds + PG8_SA(b, h) + aoff + m * 2048 + k * 1024); } while (0)
; #define PG8_LDB(dst, b, h) do { _Pragma("unroll") for (int n = 0; n < 2; ++n) _Pragma("unroll") for (int k = 0; k < 2; ++k) dst[n][k] = *(const PG8_LAS bf16x8*)(lds + PG8_SB(b, h) + boff + n * 2048 + k * 1024); } while (0)
; #define PG8_MMA(ai, bj, At, Bt) do { __builtin_amdgcn_s_setprio(1); _Pragma("unroll") for (int m = 0; m < 4; ++m) _Pragma("unroll") for (int n = 0; n < 2; ++n) _Pragma("unroll") for (int k = 0; k < 2; ++k) \
;         acc[ai][bj][m][n] = __builtin_amdgcn_mfma_f32_16x16x32_bf16(Bt[n][k], At[m][k], acc[ai][bj][m][n], 0, 0, 0); __builtin_amdgcn_s_setprio(0); } while (0)
; #define PG8_WAIT_V(n) asm volatile("s_waitcnt vmcnt(" #n ")" ::: "memory")
; #define PG8_WAIT_L(n) asm volatile("s_waitcnt lgkmcnt(" #n ")" ::: "memory")
; #define PG8_BAR __builtin_amdgcn_s_barrier()
; #define PG8_SCHED __builtin_amdgcn_sched_barrier(0)
; template <class Epi, class Sched, bool ALIGN_EPI = false, bool SP2 = false>
; __device__ __forceinline__ void gemm_phase(PG8_LAS unsigned char* lds, const Gemm g, const Sched& S, const Epi& E) {
;     ...
;             PG8_LDB(B0, 1, 0); PG8_LDB(B1, 1, 1); PG8_SCHED; PG8_LDA(At, 1, 0); PG8_STAGE(PG8_SA(0, 1), a2 + hstep, voffA);
;             PG8_WAIT_V(8); PG8_WAIT_L(0); PG8_BAR; PG8_MMA(0, 0, At, B0); PG8_MMA(0, 1, At, B1); PG8_BAR; PG8_SCHED;
;             PG8_LDA(At, 1, 1); PG8_STAGE(PG8_SB(1, 0), b3, voffB); PG8_STAGE(PG8_SB(1, 1), b3 + hstep, voffB); PG8_STAGE(PG8_SA(1, 0), a3, voffA);
	s_add_i32 s38, 0, 0x18000
	s_add_i32 s39, 0, 0x1c000
	ds_read_b128 v[74:77], v244 offset:32768
	ds_read_b128 v[78:81], v244 offset:33792
	ds_read_b128 v[98:101], v244 offset:34816
	ds_read_b128 v[102:105], v244 offset:35840
	ds_read_b128 v[146:149], v244 offset:49152
	ds_read_b128 v[150:153], v244 offset:50176
	ds_read_b128 v[154:157], v244 offset:51200
	ds_read_b128 v[158:161], v244 offset:52224
	s_add_u32 s4, s10, 0x160000
	s_addc_u32 s5, s11, 0
	s_mov_b32 m0, s18
	ds_read_b128 v[178:181], v194 offset:32768
	ds_read_b128 v[182:185], v194 offset:33792
	ds_read_b128 v[186:189], v194 offset:34816
	ds_read_b128 v[196:199], v194 offset:35840
	ds_read_b128 v[200:203], v194 offset:36864
	ds_read_b128 v[204:207], v194 offset:37888
	ds_read_b128 v[208:211], v194 offset:38912
	ds_read_b128 v[212:215], v194 offset:39936
	s_nop 0
	global_load_lds_dwordx4 v1, s[4:5]
	s_mov_b32 m0, s19
	s_nop 0
	global_load_lds_dwordx4 v164, s[4:5]
	s_waitcnt vmcnt(8)
	s_waitcnt lgkmcnt(0)
	s_barrier
	s_setprio 1
	s_waitcnt lgkmcnt(0)
	v_mfma_f32_16x16x32_bf16 v[142:145], v[74:77], v[178:181], v[142:145]
	v_mfma_f32_16x16x32_bf16 v[142:145], v[78:81], v[182:185], v[142:145]
	v_mfma_f32_16x16x32_bf16 v[138:141], v[98:101], v[178:181], v[138:141]
	v_mfma_f32_16x16x32_bf16 v[138:141], v[102:105], v[182:185], v[138:141]
	v_mfma_f32_16x16x32_bf16 v[70:73], v[146:149], v[178:181], v[70:73]
	v_mfma_f32_16x16x32_bf16 v[70:73], v[150:153], v[182:185], v[70:73]
	v_mfma_f32_16x16x32_bf16 v[66:69], v[154:157], v[178:181], v[66:69]
	v_mfma_f32_16x16x32_bf16 v[66:69], v[158:161], v[182:185], v[66:69]
	v_mfma_f32_16x16x32_bf16 v[134:137], v[74:77], v[186:189], v[134:137]
	v_mfma_f32_16x16x32_bf16 v[134:137], v[78:81], v[196:199], v[134:137]
	v_mfma_f32_16x16x32_bf16 v[130:133], v[98:101], v[186:189], v[130:133]
	v_mfma_f32_16x16x32_bf16 v[130:133], v[102:105], v[196:199], v[130:133]
	v_mfma_f32_16x16x32_bf16 v[62:65], v[146:149], v[186:189], v[62:65]
	v_mfma_f32_16x16x32_bf16 v[62:65], v[150:153], v[196:199], v[62:65]
	v_mfma_f32_16x16x32_bf16 v[58:61], v[154:157], v[186:189], v[58:61]
	v_mfma_f32_16x16x32_bf16 v[58:61], v[158:161], v[196:199], v[58:61]
	v_mfma_f32_16x16x32_bf16 v[126:129], v[74:77], v[200:203], v[126:129]
	v_mfma_f32_16x16x32_bf16 v[126:129], v[78:81], v[204:207], v[126:129]
	v_mfma_f32_16x16x32_bf16 v[122:125], v[98:101], v[200:203], v[122:125]
	v_mfma_f32_16x16x32_bf16 v[122:125], v[102:105], v[204:207], v[122:125]
	v_mfma_f32_16x16x32_bf16 v[54:57], v[146:149], v[200:203], v[54:57]
	v_mfma_f32_16x16x32_bf16 v[54:57], v[150:153], v[204:207], v[54:57]
	v_mfma_f32_16x16x32_bf16 v[50:53], v[154:157], v[200:203], v[50:53]
	v_mfma_f32_16x16x32_bf16 v[50:53], v[158:161], v[204:207], v[50:53]
	v_mfma_f32_16x16x32_bf16 v[118:121], v[74:77], v[208:211], v[118:121]
	v_mfma_f32_16x16x32_bf16 v[118:121], v[78:81], v[212:215], v[118:121]
	v_mfma_f32_16x16x32_bf16 v[114:117], v[98:101], v[208:211], v[114:117]
	v_mfma_f32_16x16x32_bf16 v[114:117], v[102:105], v[212:215], v[114:117]
	v_mfma_f32_16x16x32_bf16 v[46:49], v[146:149], v[208:211], v[46:49]
	v_mfma_f32_16x16x32_bf16 v[46:49], v[150:153], v[212:215], v[46:49]
	v_mfma_f32_16x16x32_bf16 v[42:45], v[154:157], v[208:211], v[42:45]
	v_mfma_f32_16x16x32_bf16 v[42:45], v[158:161], v[212:215], v[42:45]
	s_setprio 0
	s_barrier
	s_add_u32 s4, s8, 0x80
	s_addc_u32 s5, s9, 0
	s_add_i32 s10, s38, s15
	ds_read_b128 v[178:181], v194 offset:49152
	ds_read_b128 v[182:185], v194 offset:50176
	ds_read_b128 v[186:189], v194 offset:51200
	ds_read_b128 v[196:199], v194 offset:52224
	ds_read_b128 v[200:203], v194 offset:53248
	ds_read_b128 v[204:207], v194 offset:54272
	ds_read_b128 v[208:211], v194 offset:55296
	ds_read_b128 v[212:215], v194 offset:56320
	s_mov_b32 m0, s10
	s_nop 0
	global_load_lds_dwordx4 v162, s[4:5]
	s_add_i32 m0, s10, 0x2000
	s_nop 0
	global_load_lds_dwordx4 v190, s[4:5]
	s_add_u32 s4, s8, 0x160080
	s_addc_u32 s5, s9, 0
	s_add_i32 s8, s39, s15
	s_mov_b32 m0, s8
	s_nop 0
	global_load_lds_dwordx4 v162, s[4:5]
	s_add_i32 m0, s8, 0x2000
	s_nop 0
	global_load_lds_dwordx4 v190, s[4:5]
	s_mov_b32 m0, s24
	s_nop 0
	global_load_lds_dwordx4 v1, s[6:7]
	s_mov_b32 m0, s25
	s_nop 0
	global_load_lds_dwordx4 v164, s[6:7]
	s_waitcnt vmcnt(8)
	s_waitcnt lgkmcnt(0)
	s_barrier
; #define PG8_LDA(dst, b, h) do { _Pragma("unroll") for (int m = 0; m < 4; ++m) _Pragma("unroll") for (int k = 0; k < 2; ++k) dst[m][k] = *(const PG8_LAS bf16x8*)(lds + PG8_SA(b, h) + aoff + m * 2048 + k * 1024); } while (0)
;     __device__ __forceinline__ void operator()(const f32x4 (&acc)[2][2][4][2], const Unit& u, int wr, int wc, int fr, int fq) const {
;         const int row0 = u.pm * BM + wr * 64 + fr, col0 = u.pn * BM + wc * 32 + 8 * fq, b = (u.pm * BM) / rows_per_batch;
;         const float* g = gate + (size_t)b * gate_bstride + col0;
;         float ssq[2][4];
; #pragma unroll
;         for (int ai = 0; ai < 2; ++ai)
; #pragma unroll
;             for (int m = 0; m < 4; ++m) ssq[ai][m] = 0.f;
;         f32x4 gv[2][2], Gv[2][2];
; #pragma unroll
;         for (int bj = 0; bj < 2; ++bj) { gv[bj][0] = *(const f32x4*)(g + bj * HALF); gv[bj][1] = *(const f32x4*)(g + bj * HALF + 4); Gv[bj][0] = (f32x4){0.f, 0.f, 0.f, 0.f}; Gv[bj][1] = (f32x4){0.f, 0.f, 0.f, 0.f};
;             if (Hn) { const float* sc = scnext + (size_t)b * gate_bstride + col0 + bj * HALF;
;                 Gv[bj][0] = *(const f32x4*)(gnext + col0 + bj * HALF) * (1.0f + *(const f32x4*)(sc)); Gv[bj][1] = *(const f32x4*)(gnext + col0 + bj * HALF + 4) * (1.0f + *(const f32x4*)(sc + 4)); } }
; template <class Epi, class Sched, bool ALIGN_EPI = false, bool SP2 = false>
; __device__ __forceinline__ void gemm_phase(PG8_LAS unsigned char* lds, const Gemm g, const Sched& S, const Epi& E) {
;     ...
;             PG8_WAIT_V(8); PG8_WAIT_L(0); PG8_BAR; PG8_MMA(0, 0, At, B0); PG8_MMA(0, 1, At, B1); PG8_BAR; PG8_SCHED;
;             PG8_LDA(At, 0, 1); PG8_STAGE(PG8_SB(0, 0), b2, voffB); PG8_STAGE(PG8_SB(0, 1), b2 + hstep, voffB); PG8_STAGE(PG8_SA(0, 0), a2, voffA);
;             PG8_WAIT_V(8); PG8_WAIT_L(0); PG8_BAR; PG8_MMA(1, 0, At, B0); PG8_MMA(1, 1, At, B1); PG8_BAR; PG8_SCHED;
;             PG8_LDB(B0, 1, 0); PG8_LDB(B1, 1, 1); PG8_SCHED; PG8_LDA(At, 1, 0); PG8_STAGE(PG8_SA(0, 1), a2 + hstep, voffA);
;             PG8_WAIT_V(8); PG8_WAIT_L(0); PG8_BAR; PG8_MMA(0, 0, At, B0); PG8_MMA(0, 1, At, B1); PG8_BAR; PG8_SCHED;
;             PG8_LDA(At, 1, 1); PG8_STAGE(PG8_SB(1, 0), b3, voffB); PG8_STAGE(PG8_SB(1, 1), b3 + hstep, voffB); PG8_STAGE(PG8_SA(1, 0), a3, voffA);
;             PG8_WAIT_V(8); PG8_WAIT_L(0); PG8_BAR; PG8_MMA(1, 0, At, B0); PG8_MMA(1, 1, At, B1); PG8_BAR; PG8_SCHED;
	s_setprio 1
	s_waitcnt lgkmcnt(0)
	v_mfma_f32_16x16x32_bf16 v[110:113], v[74:77], v[178:181], v[110:113]
	v_mfma_f32_16x16x32_bf16 v[110:113], v[78:81], v[182:185], v[110:113]
	v_mfma_f32_16x16x32_bf16 v[106:109], v[98:101], v[178:181], v[106:109]
	v_mfma_f32_16x16x32_bf16 v[106:109], v[102:105], v[182:185], v[106:109]
	v_mfma_f32_16x16x32_bf16 v[30:33], v[146:149], v[178:181], v[30:33]
	v_mfma_f32_16x16x32_bf16 v[30:33], v[150:153], v[182:185], v[30:33]
	v_mfma_f32_16x16x32_bf16 v[26:29], v[154:157], v[178:181], v[26:29]
	v_mfma_f32_16x16x32_bf16 v[26:29], v[158:161], v[182:185], v[26:29]
	v_mfma_f32_16x16x32_bf16 v[94:97], v[74:77], v[186:189], v[94:97]
	v_mfma_f32_16x16x32_bf16 v[94:97], v[78:81], v[196:199], v[94:97]
	v_mfma_f32_16x16x32_bf16 v[90:93], v[98:101], v[186:189], v[90:93]
	v_mfma_f32_16x16x32_bf16 v[90:93], v[102:105], v[196:199], v[90:93]
	v_mfma_f32_16x16x32_bf16 v[22:25], v[146:149], v[186:189], v[22:25]
	v_mfma_f32_16x16x32_bf16 v[22:25], v[150:153], v[196:199], v[22:25]
	v_mfma_f32_16x16x32_bf16 v[18:21], v[154:157], v[186:189], v[18:21]
	v_mfma_f32_16x16x32_bf16 v[18:21], v[158:161], v[196:199], v[18:21]
	v_mfma_f32_16x16x32_bf16 v[86:89], v[74:77], v[200:203], v[86:89]
	v_mfma_f32_16x16x32_bf16 v[86:89], v[78:81], v[204:207], v[86:89]
	v_mfma_f32_16x16x32_bf16 v[82:85], v[98:101], v[200:203], v[82:85]
	v_mfma_f32_16x16x32_bf16 v[82:85], v[102:105], v[204:207], v[82:85]
	v_mfma_f32_16x16x32_bf16 v[14:17], v[146:149], v[200:203], v[14:17]
	v_mfma_f32_16x16x32_bf16 v[14:17], v[150:153], v[204:207], v[14:17]
	v_mfma_f32_16x16x32_bf16 v[10:13], v[154:157], v[200:203], v[10:13]
	v_mfma_f32_16x16x32_bf16 v[10:13], v[158:161], v[204:207], v[10:13]
	v_mfma_f32_16x16x32_bf16 v[34:37], v[74:77], v[208:211], v[34:37]
	v_mfma_f32_16x16x32_bf16 v[78:81], v[78:81], v[212:215], v[34:37]
	v_mfma_f32_16x16x32_bf16 v[34:37], v[98:101], v[208:211], v[38:41]
	v_mfma_f32_16x16x32_bf16 v[74:77], v[102:105], v[212:215], v[34:37]
	v_mfma_f32_16x16x32_bf16 v[6:9], v[146:149], v[208:211], v[6:9]
	v_mfma_f32_16x16x32_bf16 v[6:9], v[150:153], v[212:215], v[6:9]
	v_mfma_f32_16x16x32_bf16 v[2:5], v[154:157], v[208:211], v[2:5]
	v_mfma_f32_16x16x32_bf16 v[2:5], v[158:161], v[212:215], v[2:5]
	s_setprio 0
	s_barrier
	s_add_i32 s35, s35, 2
	s_add_u32 s31, s31, 0x100
	s_addc_u32 s34, s34, 0
	s_cmpk_gt_u32 s35, 0x55
	s_mov_b64 s[4:5], s[2:3]
	s_cbranch_scc0 .LBB0_707
	s_ashr_i32 s2, s29, 31
	s_lshr_b32 s2, s2, 27
	s_add_i32 s2, s29, s2
	s_ashr_i32 s2, s2, 5
	v_lshl_or_b32 v156, s30, 8, v193
	s_mul_i32 s5, s2, 0xc000
	v_ashrrev_i32_e32 v157, 31, v156
	s_mul_hi_i32 s4, s2, 0xc000
	s_add_u32 s2, s20, s5
	s_addc_u32 s3, s21, s4
	v_lshlrev_b64 v[34:35], 2, v[156:157]
	v_lshl_add_u64 v[38:39], s[2:3], 0, v[34:35]
	global_load_dwordx4 v[98:101], v[38:39], off offset:16
	global_load_dwordx4 v[102:105], v[38:39], off
	s_add_u32 s2, s22, s5
	s_addc_u32 s3, s23, s4
	v_lshl_add_u64 v[148:149], s[2:3], 0, v[34:35]
	v_lshl_add_u64 v[146:147], s[48:49], 0, v[34:35]
	v_mov_b32_e32 v158, 0
	v_cndmask_b32_e64 v34, 0, 1, s[46:47]
	v_cmp_ne_u32_e64 s[2:3], 1, v34
	s_andn2_b64 vcc, exec, s[46:47]
	v_mov_b32_e32 v159, v158
	v_mov_b32_e32 v160, v158
	v_mov_b32_e32 v161, v158
	v_mov_b32_e32 v178, v158
	v_mov_b32_e32 v179, v158
	v_mov_b32_e32 v180, v158
	v_mov_b32_e32 v181, v158
	s_cbranch_vccnz .LBB0_710
	global_load_dwordx4 v[34:37], v[148:149], off
	global_load_dwordx4 v[150:153], v[148:149], off offset:16
	global_load_dwordx4 v[158:161], v[146:147], off
	global_load_dwordx4 v[178:181], v[146:147], off offset:16
	s_waitcnt vmcnt(0)
	v_pk_add_f32 v[36:37], v[36:37], 1.0 op_sel_hi:[1,0]
	v_pk_add_f32 v[34:35], v[34:35], 1.0 op_sel_hi:[1,0]
	v_pk_add_f32 v[40:41], v[152:153], 1.0 op_sel_hi:[1,0]
	v_pk_add_f32 v[150:151], v[150:151], 1.0 op_sel_hi:[1,0]
	v_pk_mul_f32 v[160:161], v[160:161], v[36:37]
	v_pk_mul_f32 v[158:159], v[158:159], v[34:35]
	v_pk_mul_f32 v[180:181], v[180:181], v[40:41]
	v_pk_mul_f32 v[178:179], v[178:179], v[150:151]
